# up-projection epilogue: the gelu polynomial head (x*(c1+c2*x^2), +1) is computed with packed f32 ops per feature pair instead of scalar ops (same f32 math, exp/rcp unchanged)
# speedup vs baseline: 1.0030x; 1.0004x over previous
.LBB0_601:
	s_lshl_b32 s4, s42, 8
	s_add_i32 s4, s4, s94
	v_or_b32_e32 v172, s4, v200
	v_lshl_or_b32 v174, s39, 8, v203
	s_cmp_lt_i32 s23, 2
	s_mov_b64 s[0:1], -1
	s_cbranch_scc1 .LBB0_641
	s_cmp_gt_i32 s23, 2
	s_cbranch_scc0 .LBB0_638
	v_mov_b32_e32 v214, 0x3dd2d3e8
	v_mov_b32_e32 v215, 0x3dd2d3e8
	v_mov_b32_e32 v216, 0x40135761
	v_mov_b32_e32 v217, 0x40135761
	v_mov_b32_e32 v218, 1.0
	v_mov_b32_e32 v219, 1.0
	v_lshl_or_b32 v176, s39, 7, v203
	v_ashrrev_i32_e32 v177, 31, v176
	v_readlane_b32 s0, v254, 21
	v_lshlrev_b64 v[142:143], 2, v[176:177]
	v_readlane_b32 s1, v254, 22
	v_lshl_add_u64 v[180:181], s[62:63], 0, v[142:143]
	global_load_dwordx4 v[146:149], v[180:181], off
	v_lshl_add_u64 v[130:131], s[0:1], 0, v[142:143]
	v_readlane_b32 s0, v254, 43
	v_readlane_b32 s1, v254, 44
	v_lshl_add_u64 v[132:133], s[68:69], 0, v[142:143]
	global_load_dwordx4 v[150:153], v[130:131], off
	global_load_dwordx4 v[154:157], v[132:133], off
	v_lshl_add_u64 v[182:183], s[0:1], 0, v[142:143]
	v_lshl_add_u64 v[130:131], s[70:71], 0, v[142:143]
	v_lshl_add_u64 v[134:135], s[72:73], 0, v[142:143]
	v_lshl_add_u64 v[138:139], s[74:75], 0, v[142:143]
	v_lshl_add_u64 v[142:143], s[76:77], 0, v[142:143]
	global_load_dwordx4 v[158:161], v[182:183], off
	s_nop 0
	global_load_dwordx4 v[130:133], v[130:131], off
	s_nop 0
	global_load_dwordx4 v[134:137], v[134:135], off
	v_lshl_add_u64 v[178:179], v[176:177], 1, s[52:53]
	global_load_dwordx4 v[138:141], v[138:139], off
	v_mov_b32_dpp v198, v68 row_shr:2 row_mask:0xf bank_mask:0xf bound_ctrl:1
	global_load_dwordx4 v[142:145], v[142:143], off
	v_mov_b32_dpp v196, v68 row_shr:1 row_mask:0xf bank_mask:0xf bound_ctrl:1
	v_mov_b32_dpp v194, v126 row_shr:2 row_mask:0xf bank_mask:0xf bound_ctrl:1
	v_mov_b32_dpp v192, v126 row_shr:1 row_mask:0xf bank_mask:0xf bound_ctrl:1
	v_mov_b32_dpp v199, v69 row_shr:2 row_mask:0xf bank_mask:0xf bound_ctrl:1
	v_mov_b32_dpp v197, v69 row_shr:1 row_mask:0xf bank_mask:0xf bound_ctrl:1
	v_mov_b32_dpp v195, v127 row_shr:2 row_mask:0xf bank_mask:0xf bound_ctrl:1
	v_mov_b32_dpp v193, v127 row_shr:1 row_mask:0xf bank_mask:0xf bound_ctrl:1
	v_mov_b32_dpp v190, v70 row_shr:2 row_mask:0xf bank_mask:0xf bound_ctrl:1
	v_mov_b32_dpp v188, v70 row_shr:1 row_mask:0xf bank_mask:0xf bound_ctrl:1
	v_mov_b32_dpp v186, v128 row_shr:2 row_mask:0xf bank_mask:0xf bound_ctrl:1
	v_mov_b32_dpp v184, v128 row_shr:1 row_mask:0xf bank_mask:0xf bound_ctrl:1
	v_mov_b32_dpp v191, v71 row_shr:2 row_mask:0xf bank_mask:0xf bound_ctrl:1
	v_mov_b32_dpp v189, v71 row_shr:1 row_mask:0xf bank_mask:0xf bound_ctrl:1
	v_mov_b32_dpp v187, v129 row_shr:2 row_mask:0xf bank_mask:0xf bound_ctrl:1
	v_mov_b32_dpp v185, v129 row_shr:1 row_mask:0xf bank_mask:0xf bound_ctrl:1
	s_and_saveexec_b64 s[0:1], s[40:41]
	s_movk_i32 s5, 0x1600
	s_cbranch_execz .LBB0_605
	s_waitcnt vmcnt(0)
	v_pk_fma_f32 v[198:199], v[146:147], v[198:199], v[158:159]
	v_pk_fma_f32 v[190:191], v[148:149], v[190:191], v[160:161]
	v_pk_fma_f32 v[196:197], v[150:151], v[196:197], v[198:199]
	v_pk_fma_f32 v[188:189], v[152:153], v[188:189], v[190:191]
	v_pk_fma_f32 v[196:197], v[68:69], v[154:155], v[196:197]
	v_pk_fma_f32 v[188:189], v[70:71], v[156:157], v[188:189]
	v_pk_fma_f32 v[194:195], v[130:131], v[194:195], v[142:143]
	v_pk_fma_f32 v[192:193], v[134:135], v[192:193], v[194:195]
	v_pk_mul_f32 v[210:211], v[196:197], v[196:197]
	v_pk_fma_f32 v[210:211], v[210:211], v[214:215], v[216:217]
	v_pk_mul_f32 v[210:211], v[210:211], v[196:197]
	v_exp_f32_e32 v210, v210
	v_exp_f32_e32 v211, v211
	s_nop 1
	v_pk_add_f32 v[210:211], v[210:211], v[218:219]
	v_rcp_f32_e32 v198, v210
	v_rcp_f32_e32 v199, v211
	s_nop 1
	v_pk_fma_f32 v[194:195], v[196:197], v[198:199], v[196:197] neg_lo:[1,0,0] neg_hi:[1,0,0]
	v_pk_fma_f32 v[192:193], v[126:127], v[138:139], v[192:193]
	v_pk_mul_f32 v[190:191], v[192:193], v[194:195]
	v_pk_fma_f32 v[186:187], v[132:133], v[186:187], v[144:145]
	s_nop 0
	v_pk_fma_f32 v[184:185], v[136:137], v[184:185], v[186:187]
	v_pk_mul_f32 v[210:211], v[188:189], v[188:189]
	v_pk_fma_f32 v[210:211], v[210:211], v[214:215], v[216:217]
	v_pk_mul_f32 v[210:211], v[210:211], v[188:189]
	v_exp_f32_e32 v210, v210
	v_exp_f32_e32 v211, v211
	s_nop 1
	v_pk_add_f32 v[210:211], v[210:211], v[218:219]
	v_rcp_f32_e32 v192, v210
	v_rcp_f32_e32 v193, v211
	s_nop 1
	v_pk_fma_f32 v[186:187], v[188:189], v[192:193], v[188:189] neg_lo:[1,0,0] neg_hi:[1,0,0]
	v_pk_fma_f32 v[184:185], v[128:129], v[140:141], v[184:185]
	s_nop 0
	v_pk_mul_f32 v[184:185], v[184:185], v[186:187]
	v_cvt_pk_bf16_f32 v186, v190, v191
	v_cvt_pk_bf16_f32 v187, v184, v185
	v_mad_i64_i32 v[184:185], s[6:7], v172, s5, v[178:179]
	global_store_dwordx2 v[184:185], v[186:187], off
.LBB0_605:
	s_or_b64 exec, exec, s[0:1]
	s_cmp_lg_u32 s42, 64
	s_cselect_b64 exec, -1, 0
	s_nop 1
	v_mov_b32_dpp v198, v68 row_ror:2 row_mask:0xf bank_mask:0x1
	v_mov_b32_dpp v196, v68 row_ror:1 row_mask:0xf bank_mask:0x1
	v_mov_b32_dpp v194, v126 row_ror:2 row_mask:0xf bank_mask:0x1
	v_mov_b32_dpp v192, v126 row_ror:1 row_mask:0xf bank_mask:0x1
	v_mov_b32_dpp v199, v69 row_ror:2 row_mask:0xf bank_mask:0x1
	v_mov_b32_dpp v197, v69 row_ror:1 row_mask:0xf bank_mask:0x1
	v_mov_b32_dpp v195, v127 row_ror:2 row_mask:0xf bank_mask:0x1
	v_mov_b32_dpp v193, v127 row_ror:1 row_mask:0xf bank_mask:0x1
	v_mov_b32_dpp v190, v70 row_ror:2 row_mask:0xf bank_mask:0x1
	v_mov_b32_dpp v188, v70 row_ror:1 row_mask:0xf bank_mask:0x1
	v_mov_b32_dpp v186, v128 row_ror:2 row_mask:0xf bank_mask:0x1
	v_mov_b32_dpp v184, v128 row_ror:1 row_mask:0xf bank_mask:0x1
	v_mov_b32_dpp v191, v71 row_ror:2 row_mask:0xf bank_mask:0x1
	v_mov_b32_dpp v189, v71 row_ror:1 row_mask:0xf bank_mask:0x1
	v_mov_b32_dpp v187, v129 row_ror:2 row_mask:0xf bank_mask:0x1
	v_mov_b32_dpp v185, v129 row_ror:1 row_mask:0xf bank_mask:0x1
	s_mov_b64 exec, -1
	s_nop 1
	v_mov_b32_dpp v198, v52 row_shr:2 row_mask:0xf bank_mask:0xf
	v_mov_b32_dpp v196, v52 row_shr:1 row_mask:0xf bank_mask:0xf
	v_mov_b32_dpp v194, v118 row_shr:2 row_mask:0xf bank_mask:0xf
	v_mov_b32_dpp v192, v118 row_shr:1 row_mask:0xf bank_mask:0xf
	v_mov_b32_dpp v199, v53 row_shr:2 row_mask:0xf bank_mask:0xf
	v_mov_b32_dpp v197, v53 row_shr:1 row_mask:0xf bank_mask:0xf
	v_mov_b32_dpp v195, v119 row_shr:2 row_mask:0xf bank_mask:0xf
	v_mov_b32_dpp v193, v119 row_shr:1 row_mask:0xf bank_mask:0xf
	v_mov_b32_dpp v190, v54 row_shr:2 row_mask:0xf bank_mask:0xf
	v_mov_b32_dpp v188, v54 row_shr:1 row_mask:0xf bank_mask:0xf
	v_mov_b32_dpp v186, v120 row_shr:2 row_mask:0xf bank_mask:0xf
	v_mov_b32_dpp v184, v120 row_shr:1 row_mask:0xf bank_mask:0xf
	v_mov_b32_dpp v191, v55 row_shr:2 row_mask:0xf bank_mask:0xf
	v_mov_b32_dpp v189, v55 row_shr:1 row_mask:0xf bank_mask:0xf
	v_mov_b32_dpp v187, v121 row_shr:2 row_mask:0xf bank_mask:0xf
	v_mov_b32_dpp v185, v121 row_shr:1 row_mask:0xf bank_mask:0xf
	v_or_b32_e32 v175, 16, v172
	s_cmp_lg_u32 s42, 64
	s_cselect_b64 vcc, -1, s[40:41]
	s_and_saveexec_b64 s[0:1], vcc
	s_cbranch_execz .LBB0_607
	s_nop 0
	v_pk_fma_f32 v[198:199], v[146:147], v[198:199], v[158:159]
	v_pk_fma_f32 v[190:191], v[148:149], v[190:191], v[160:161]
	v_pk_fma_f32 v[196:197], v[150:151], v[196:197], v[198:199]
	v_pk_fma_f32 v[188:189], v[152:153], v[188:189], v[190:191]
	v_pk_fma_f32 v[196:197], v[52:53], v[154:155], v[196:197]
	v_pk_fma_f32 v[188:189], v[54:55], v[156:157], v[188:189]
	v_pk_fma_f32 v[194:195], v[130:131], v[194:195], v[142:143]
	v_pk_fma_f32 v[192:193], v[134:135], v[192:193], v[194:195]
	v_pk_mul_f32 v[210:211], v[196:197], v[196:197]
	v_pk_fma_f32 v[210:211], v[210:211], v[214:215], v[216:217]
	v_pk_mul_f32 v[210:211], v[210:211], v[196:197]
	v_exp_f32_e32 v210, v210
	v_exp_f32_e32 v211, v211
	s_nop 1
	v_pk_add_f32 v[210:211], v[210:211], v[218:219]
	v_rcp_f32_e32 v198, v210
	v_rcp_f32_e32 v199, v211
	s_nop 1
	v_pk_fma_f32 v[194:195], v[196:197], v[198:199], v[196:197] neg_lo:[1,0,0] neg_hi:[1,0,0]
	v_pk_fma_f32 v[192:193], v[118:119], v[138:139], v[192:193]
	v_pk_mul_f32 v[190:191], v[192:193], v[194:195]
	v_pk_fma_f32 v[186:187], v[132:133], v[186:187], v[144:145]
	s_nop 0
	v_pk_fma_f32 v[184:185], v[136:137], v[184:185], v[186:187]
	v_pk_mul_f32 v[210:211], v[188:189], v[188:189]
	v_pk_fma_f32 v[210:211], v[210:211], v[214:215], v[216:217]
	v_pk_mul_f32 v[210:211], v[210:211], v[188:189]
	v_exp_f32_e32 v210, v210
	v_exp_f32_e32 v211, v211
	s_nop 1
	v_pk_add_f32 v[210:211], v[210:211], v[218:219]
	v_rcp_f32_e32 v192, v210
	v_rcp_f32_e32 v193, v211
	s_nop 1
	v_pk_fma_f32 v[186:187], v[188:189], v[192:193], v[188:189] neg_lo:[1,0,0] neg_hi:[1,0,0]
	v_pk_fma_f32 v[184:185], v[120:121], v[140:141], v[184:185]
	s_nop 0
	v_pk_mul_f32 v[184:185], v[184:185], v[186:187]
	v_cvt_pk_bf16_f32 v186, v190, v191
	v_cvt_pk_bf16_f32 v187, v184, v185
	v_mad_i64_i32 v[184:185], s[6:7], v175, s5, v[178:179]
	global_store_dwordx2 v[184:185], v[186:187], off
.LBB0_607:
	s_or_b64 exec, exec, s[0:1]
	s_cmp_lg_u32 s42, 64
	s_cselect_b64 exec, -1, 0
	s_nop 1
	v_mov_b32_dpp v198, v52 row_ror:2 row_mask:0xf bank_mask:0x1
	v_mov_b32_dpp v196, v52 row_ror:1 row_mask:0xf bank_mask:0x1
	v_mov_b32_dpp v194, v118 row_ror:2 row_mask:0xf bank_mask:0x1
	v_mov_b32_dpp v192, v118 row_ror:1 row_mask:0xf bank_mask:0x1
	v_mov_b32_dpp v199, v53 row_ror:2 row_mask:0xf bank_mask:0x1
	v_mov_b32_dpp v197, v53 row_ror:1 row_mask:0xf bank_mask:0x1
	v_mov_b32_dpp v195, v119 row_ror:2 row_mask:0xf bank_mask:0x1
	v_mov_b32_dpp v193, v119 row_ror:1 row_mask:0xf bank_mask:0x1
	v_mov_b32_dpp v190, v54 row_ror:2 row_mask:0xf bank_mask:0x1
	v_mov_b32_dpp v188, v54 row_ror:1 row_mask:0xf bank_mask:0x1
	v_mov_b32_dpp v186, v120 row_ror:2 row_mask:0xf bank_mask:0x1
	v_mov_b32_dpp v184, v120 row_ror:1 row_mask:0xf bank_mask:0x1
	v_mov_b32_dpp v191, v55 row_ror:2 row_mask:0xf bank_mask:0x1
	v_mov_b32_dpp v189, v55 row_ror:1 row_mask:0xf bank_mask:0x1
	v_mov_b32_dpp v187, v121 row_ror:2 row_mask:0xf bank_mask:0x1
	v_mov_b32_dpp v185, v121 row_ror:1 row_mask:0xf bank_mask:0x1
	s_mov_b64 exec, -1
	s_nop 1
	v_mov_b32_dpp v198, v44 row_shr:2 row_mask:0xf bank_mask:0xf
	v_mov_b32_dpp v196, v44 row_shr:1 row_mask:0xf bank_mask:0xf
	v_mov_b32_dpp v194, v108 row_shr:2 row_mask:0xf bank_mask:0xf
	v_mov_b32_dpp v192, v108 row_shr:1 row_mask:0xf bank_mask:0xf
	v_mov_b32_dpp v199, v45 row_shr:2 row_mask:0xf bank_mask:0xf
	v_mov_b32_dpp v197, v45 row_shr:1 row_mask:0xf bank_mask:0xf
	v_mov_b32_dpp v195, v109 row_shr:2 row_mask:0xf bank_mask:0xf
	v_mov_b32_dpp v193, v109 row_shr:1 row_mask:0xf bank_mask:0xf
	v_mov_b32_dpp v190, v46 row_shr:2 row_mask:0xf bank_mask:0xf
	v_mov_b32_dpp v188, v46 row_shr:1 row_mask:0xf bank_mask:0xf
	v_mov_b32_dpp v186, v110 row_shr:2 row_mask:0xf bank_mask:0xf
	v_mov_b32_dpp v184, v110 row_shr:1 row_mask:0xf bank_mask:0xf
	v_mov_b32_dpp v191, v47 row_shr:2 row_mask:0xf bank_mask:0xf
	v_mov_b32_dpp v189, v47 row_shr:1 row_mask:0xf bank_mask:0xf
	v_mov_b32_dpp v187, v111 row_shr:2 row_mask:0xf bank_mask:0xf
	v_mov_b32_dpp v185, v111 row_shr:1 row_mask:0xf bank_mask:0xf
	v_or_b32_e32 v205, 32, v172
	s_cmp_lg_u32 s42, 64
	s_cselect_b64 vcc, -1, s[40:41]
	s_and_saveexec_b64 s[0:1], vcc
	s_cbranch_execz .LBB0_609
	s_nop 0
	v_pk_fma_f32 v[198:199], v[146:147], v[198:199], v[158:159]
	v_pk_fma_f32 v[190:191], v[148:149], v[190:191], v[160:161]
	v_pk_fma_f32 v[196:197], v[150:151], v[196:197], v[198:199]
	v_pk_fma_f32 v[188:189], v[152:153], v[188:189], v[190:191]
	v_pk_fma_f32 v[196:197], v[44:45], v[154:155], v[196:197]
	v_pk_fma_f32 v[188:189], v[46:47], v[156:157], v[188:189]
	v_pk_fma_f32 v[194:195], v[130:131], v[194:195], v[142:143]
	v_pk_fma_f32 v[192:193], v[134:135], v[192:193], v[194:195]
	v_pk_mul_f32 v[210:211], v[196:197], v[196:197]
	v_pk_fma_f32 v[210:211], v[210:211], v[214:215], v[216:217]
	v_pk_mul_f32 v[210:211], v[210:211], v[196:197]
	v_exp_f32_e32 v210, v210
	v_exp_f32_e32 v211, v211
	s_nop 1
	v_pk_add_f32 v[210:211], v[210:211], v[218:219]
	v_rcp_f32_e32 v198, v210
	v_rcp_f32_e32 v199, v211
	s_nop 1
	v_pk_fma_f32 v[194:195], v[196:197], v[198:199], v[196:197] neg_lo:[1,0,0] neg_hi:[1,0,0]
	v_pk_fma_f32 v[192:193], v[108:109], v[138:139], v[192:193]
	v_pk_mul_f32 v[190:191], v[192:193], v[194:195]
	v_pk_fma_f32 v[186:187], v[132:133], v[186:187], v[144:145]
	s_nop 0
	v_pk_fma_f32 v[184:185], v[136:137], v[184:185], v[186:187]
	v_pk_mul_f32 v[210:211], v[188:189], v[188:189]
	v_pk_fma_f32 v[210:211], v[210:211], v[214:215], v[216:217]
	v_pk_mul_f32 v[210:211], v[210:211], v[188:189]
	v_exp_f32_e32 v210, v210
	v_exp_f32_e32 v211, v211
	s_nop 1
	v_pk_add_f32 v[210:211], v[210:211], v[218:219]
	v_rcp_f32_e32 v192, v210
	v_rcp_f32_e32 v193, v211
	s_nop 1
	v_pk_fma_f32 v[186:187], v[188:189], v[192:193], v[188:189] neg_lo:[1,0,0] neg_hi:[1,0,0]
	v_pk_fma_f32 v[184:185], v[110:111], v[140:141], v[184:185]
	s_nop 0
	v_pk_mul_f32 v[184:185], v[184:185], v[186:187]
	v_cvt_pk_bf16_f32 v186, v190, v191
	v_cvt_pk_bf16_f32 v187, v184, v185
	v_mad_i64_i32 v[184:185], s[6:7], v205, s5, v[178:179]
	global_store_dwordx2 v[184:185], v[186:187], off
.LBB0_609:
	s_or_b64 exec, exec, s[0:1]
	s_cmp_lg_u32 s42, 64
	s_cselect_b64 exec, -1, 0
	s_nop 1
	v_mov_b32_dpp v198, v44 row_ror:2 row_mask:0xf bank_mask:0x1
	v_mov_b32_dpp v196, v44 row_ror:1 row_mask:0xf bank_mask:0x1
	v_mov_b32_dpp v194, v108 row_ror:2 row_mask:0xf bank_mask:0x1
	v_mov_b32_dpp v192, v108 row_ror:1 row_mask:0xf bank_mask:0x1
	v_mov_b32_dpp v199, v45 row_ror:2 row_mask:0xf bank_mask:0x1
	v_mov_b32_dpp v197, v45 row_ror:1 row_mask:0xf bank_mask:0x1
	v_mov_b32_dpp v195, v109 row_ror:2 row_mask:0xf bank_mask:0x1
	v_mov_b32_dpp v193, v109 row_ror:1 row_mask:0xf bank_mask:0x1
	v_mov_b32_dpp v190, v46 row_ror:2 row_mask:0xf bank_mask:0x1
	v_mov_b32_dpp v188, v46 row_ror:1 row_mask:0xf bank_mask:0x1
	v_mov_b32_dpp v186, v110 row_ror:2 row_mask:0xf bank_mask:0x1
	v_mov_b32_dpp v184, v110 row_ror:1 row_mask:0xf bank_mask:0x1
	v_mov_b32_dpp v191, v47 row_ror:2 row_mask:0xf bank_mask:0x1
	v_mov_b32_dpp v189, v47 row_ror:1 row_mask:0xf bank_mask:0x1
	v_mov_b32_dpp v187, v111 row_ror:2 row_mask:0xf bank_mask:0x1
	v_mov_b32_dpp v185, v111 row_ror:1 row_mask:0xf bank_mask:0x1
	s_mov_b64 exec, -1
	s_nop 1
	v_mov_b32_dpp v198, v36 row_shr:2 row_mask:0xf bank_mask:0xf
	v_mov_b32_dpp v196, v36 row_shr:1 row_mask:0xf bank_mask:0xf
	v_mov_b32_dpp v194, v100 row_shr:2 row_mask:0xf bank_mask:0xf
	v_mov_b32_dpp v192, v100 row_shr:1 row_mask:0xf bank_mask:0xf
	v_mov_b32_dpp v199, v37 row_shr:2 row_mask:0xf bank_mask:0xf
	v_mov_b32_dpp v197, v37 row_shr:1 row_mask:0xf bank_mask:0xf
	v_mov_b32_dpp v195, v101 row_shr:2 row_mask:0xf bank_mask:0xf
	v_mov_b32_dpp v193, v101 row_shr:1 row_mask:0xf bank_mask:0xf
	v_mov_b32_dpp v190, v38 row_shr:2 row_mask:0xf bank_mask:0xf
	v_mov_b32_dpp v188, v38 row_shr:1 row_mask:0xf bank_mask:0xf
	v_mov_b32_dpp v186, v102 row_shr:2 row_mask:0xf bank_mask:0xf
	v_mov_b32_dpp v184, v102 row_shr:1 row_mask:0xf bank_mask:0xf
	v_mov_b32_dpp v191, v39 row_shr:2 row_mask:0xf bank_mask:0xf
	v_mov_b32_dpp v189, v39 row_shr:1 row_mask:0xf bank_mask:0xf
	v_mov_b32_dpp v187, v103 row_shr:2 row_mask:0xf bank_mask:0xf
	v_mov_b32_dpp v185, v103 row_shr:1 row_mask:0xf bank_mask:0xf
	v_or_b32_e32 v206, 48, v172
	s_cmp_lg_u32 s42, 64
	s_cselect_b64 vcc, -1, s[40:41]
	s_and_saveexec_b64 s[0:1], vcc
	s_cbranch_execz .LBB0_611
	s_nop 0
	v_pk_fma_f32 v[198:199], v[146:147], v[198:199], v[158:159]
	v_pk_fma_f32 v[190:191], v[148:149], v[190:191], v[160:161]
	v_pk_fma_f32 v[196:197], v[150:151], v[196:197], v[198:199]
	v_pk_fma_f32 v[188:189], v[152:153], v[188:189], v[190:191]
	v_pk_fma_f32 v[196:197], v[36:37], v[154:155], v[196:197]
	v_pk_fma_f32 v[188:189], v[38:39], v[156:157], v[188:189]
	v_pk_fma_f32 v[194:195], v[130:131], v[194:195], v[142:143]
	v_pk_fma_f32 v[192:193], v[134:135], v[192:193], v[194:195]
	v_pk_mul_f32 v[210:211], v[196:197], v[196:197]
	v_pk_fma_f32 v[210:211], v[210:211], v[214:215], v[216:217]
	v_pk_mul_f32 v[210:211], v[210:211], v[196:197]
	v_exp_f32_e32 v210, v210
	v_exp_f32_e32 v211, v211
	s_nop 1
	v_pk_add_f32 v[210:211], v[210:211], v[218:219]
	v_rcp_f32_e32 v198, v210
	v_rcp_f32_e32 v199, v211
	s_nop 1
	v_pk_fma_f32 v[194:195], v[196:197], v[198:199], v[196:197] neg_lo:[1,0,0] neg_hi:[1,0,0]
	v_pk_fma_f32 v[192:193], v[100:101], v[138:139], v[192:193]
	v_pk_mul_f32 v[190:191], v[192:193], v[194:195]
	v_pk_fma_f32 v[186:187], v[132:133], v[186:187], v[144:145]
	s_nop 0
	v_pk_fma_f32 v[184:185], v[136:137], v[184:185], v[186:187]
	v_pk_mul_f32 v[210:211], v[188:189], v[188:189]
	v_pk_fma_f32 v[210:211], v[210:211], v[214:215], v[216:217]
	v_pk_mul_f32 v[210:211], v[210:211], v[188:189]
	v_exp_f32_e32 v210, v210
	v_exp_f32_e32 v211, v211
	s_nop 1
	v_pk_add_f32 v[210:211], v[210:211], v[218:219]
	v_rcp_f32_e32 v192, v210
	v_rcp_f32_e32 v193, v211
	s_nop 1
	v_pk_fma_f32 v[186:187], v[188:189], v[192:193], v[188:189] neg_lo:[1,0,0] neg_hi:[1,0,0]
	v_pk_fma_f32 v[184:185], v[102:103], v[140:141], v[184:185]
	s_nop 0
	v_pk_mul_f32 v[184:185], v[184:185], v[186:187]
	v_cvt_pk_bf16_f32 v186, v190, v191
	v_cvt_pk_bf16_f32 v187, v184, v185
	v_mad_i64_i32 v[184:185], s[6:7], v206, s5, v[178:179]
	global_store_dwordx2 v[184:185], v[186:187], off
.LBB0_611:
	s_or_b64 exec, exec, s[0:1]
	v_add_u32_e32 v173, 0x80, v172
	v_mov_b32_dpp v198, v28 row_shr:2 row_mask:0xf bank_mask:0xf bound_ctrl:1
	v_mov_b32_dpp v196, v28 row_shr:1 row_mask:0xf bank_mask:0xf bound_ctrl:1
	v_mov_b32_dpp v194, v92 row_shr:2 row_mask:0xf bank_mask:0xf bound_ctrl:1
	v_mov_b32_dpp v192, v92 row_shr:1 row_mask:0xf bank_mask:0xf bound_ctrl:1
	v_mov_b32_dpp v199, v29 row_shr:2 row_mask:0xf bank_mask:0xf bound_ctrl:1
	v_mov_b32_dpp v197, v29 row_shr:1 row_mask:0xf bank_mask:0xf bound_ctrl:1
	v_mov_b32_dpp v195, v93 row_shr:2 row_mask:0xf bank_mask:0xf bound_ctrl:1
	v_mov_b32_dpp v193, v93 row_shr:1 row_mask:0xf bank_mask:0xf bound_ctrl:1
	v_mov_b32_dpp v190, v30 row_shr:2 row_mask:0xf bank_mask:0xf bound_ctrl:1
	v_mov_b32_dpp v188, v30 row_shr:1 row_mask:0xf bank_mask:0xf bound_ctrl:1
	v_mov_b32_dpp v186, v94 row_shr:2 row_mask:0xf bank_mask:0xf bound_ctrl:1
	v_mov_b32_dpp v184, v94 row_shr:1 row_mask:0xf bank_mask:0xf bound_ctrl:1
	v_mov_b32_dpp v191, v31 row_shr:2 row_mask:0xf bank_mask:0xf bound_ctrl:1
	v_mov_b32_dpp v189, v31 row_shr:1 row_mask:0xf bank_mask:0xf bound_ctrl:1
	v_mov_b32_dpp v187, v95 row_shr:2 row_mask:0xf bank_mask:0xf bound_ctrl:1
	v_mov_b32_dpp v185, v95 row_shr:1 row_mask:0xf bank_mask:0xf bound_ctrl:1
	s_and_saveexec_b64 s[0:1], s[40:41]
	s_cbranch_execz .LBB0_613
	s_nop 0
	v_pk_fma_f32 v[198:199], v[146:147], v[198:199], v[158:159]
	v_pk_fma_f32 v[190:191], v[148:149], v[190:191], v[160:161]
	v_pk_fma_f32 v[196:197], v[150:151], v[196:197], v[198:199]
	v_pk_fma_f32 v[188:189], v[152:153], v[188:189], v[190:191]
	v_pk_fma_f32 v[196:197], v[28:29], v[154:155], v[196:197]
	v_pk_fma_f32 v[188:189], v[30:31], v[156:157], v[188:189]
	v_pk_fma_f32 v[194:195], v[130:131], v[194:195], v[142:143]
	v_pk_fma_f32 v[192:193], v[134:135], v[192:193], v[194:195]
	v_pk_mul_f32 v[210:211], v[196:197], v[196:197]
	v_pk_fma_f32 v[210:211], v[210:211], v[214:215], v[216:217]
	v_pk_mul_f32 v[210:211], v[210:211], v[196:197]
	v_exp_f32_e32 v210, v210
	v_exp_f32_e32 v211, v211
	s_nop 1
	v_pk_add_f32 v[210:211], v[210:211], v[218:219]
	v_rcp_f32_e32 v198, v210
	v_rcp_f32_e32 v199, v211
	s_nop 1
	v_pk_fma_f32 v[194:195], v[196:197], v[198:199], v[196:197] neg_lo:[1,0,0] neg_hi:[1,0,0]
	v_pk_fma_f32 v[192:193], v[92:93], v[138:139], v[192:193]
	v_pk_fma_f32 v[186:187], v[132:133], v[186:187], v[144:145]
	v_pk_mul_f32 v[190:191], v[192:193], v[194:195]
	v_pk_fma_f32 v[184:185], v[136:137], v[184:185], v[186:187]
	v_pk_mul_f32 v[210:211], v[188:189], v[188:189]
	v_pk_fma_f32 v[210:211], v[210:211], v[214:215], v[216:217]
	v_pk_mul_f32 v[210:211], v[210:211], v[188:189]
	v_exp_f32_e32 v210, v210
	v_exp_f32_e32 v211, v211
	s_nop 1
	v_pk_add_f32 v[210:211], v[210:211], v[218:219]
	v_rcp_f32_e32 v192, v210
	v_rcp_f32_e32 v193, v211
	s_nop 1
	v_pk_fma_f32 v[186:187], v[188:189], v[192:193], v[188:189] neg_lo:[1,0,0] neg_hi:[1,0,0]
	v_pk_fma_f32 v[184:185], v[94:95], v[140:141], v[184:185]
	s_nop 0
	v_pk_mul_f32 v[184:185], v[184:185], v[186:187]
	v_cvt_pk_bf16_f32 v186, v190, v191
	v_cvt_pk_bf16_f32 v187, v184, v185
	v_mad_i64_i32 v[184:185], s[6:7], v173, s5, v[178:179]
	global_store_dwordx2 v[184:185], v[186:187], off
.LBB0_613:
	s_or_b64 exec, exec, s[0:1]
	s_cmp_lg_u32 s42, 64
	s_cselect_b64 exec, -1, 0
	s_nop 1
	v_mov_b32_dpp v198, v28 row_ror:2 row_mask:0xf bank_mask:0x1
	v_mov_b32_dpp v196, v28 row_ror:1 row_mask:0xf bank_mask:0x1
	v_mov_b32_dpp v194, v92 row_ror:2 row_mask:0xf bank_mask:0x1
	v_mov_b32_dpp v192, v92 row_ror:1 row_mask:0xf bank_mask:0x1
	v_mov_b32_dpp v199, v29 row_ror:2 row_mask:0xf bank_mask:0x1
	v_mov_b32_dpp v197, v29 row_ror:1 row_mask:0xf bank_mask:0x1
	v_mov_b32_dpp v195, v93 row_ror:2 row_mask:0xf bank_mask:0x1
	v_mov_b32_dpp v193, v93 row_ror:1 row_mask:0xf bank_mask:0x1
	v_mov_b32_dpp v190, v30 row_ror:2 row_mask:0xf bank_mask:0x1
	v_mov_b32_dpp v188, v30 row_ror:1 row_mask:0xf bank_mask:0x1
	v_mov_b32_dpp v186, v94 row_ror:2 row_mask:0xf bank_mask:0x1
	v_mov_b32_dpp v184, v94 row_ror:1 row_mask:0xf bank_mask:0x1
	v_mov_b32_dpp v191, v31 row_ror:2 row_mask:0xf bank_mask:0x1
	v_mov_b32_dpp v189, v31 row_ror:1 row_mask:0xf bank_mask:0x1
	v_mov_b32_dpp v187, v95 row_ror:2 row_mask:0xf bank_mask:0x1
	v_mov_b32_dpp v185, v95 row_ror:1 row_mask:0xf bank_mask:0x1
	s_mov_b64 exec, -1
	s_nop 1
	v_mov_b32_dpp v198, v20 row_shr:2 row_mask:0xf bank_mask:0xf
	v_mov_b32_dpp v196, v20 row_shr:1 row_mask:0xf bank_mask:0xf
	v_mov_b32_dpp v194, v84 row_shr:2 row_mask:0xf bank_mask:0xf
	v_mov_b32_dpp v192, v84 row_shr:1 row_mask:0xf bank_mask:0xf
	v_mov_b32_dpp v199, v21 row_shr:2 row_mask:0xf bank_mask:0xf
	v_mov_b32_dpp v197, v21 row_shr:1 row_mask:0xf bank_mask:0xf
	v_mov_b32_dpp v195, v85 row_shr:2 row_mask:0xf bank_mask:0xf
	v_mov_b32_dpp v193, v85 row_shr:1 row_mask:0xf bank_mask:0xf
	v_mov_b32_dpp v190, v22 row_shr:2 row_mask:0xf bank_mask:0xf
	v_mov_b32_dpp v188, v22 row_shr:1 row_mask:0xf bank_mask:0xf
	v_mov_b32_dpp v186, v86 row_shr:2 row_mask:0xf bank_mask:0xf
	v_mov_b32_dpp v184, v86 row_shr:1 row_mask:0xf bank_mask:0xf
	v_mov_b32_dpp v191, v23 row_shr:2 row_mask:0xf bank_mask:0xf
	v_mov_b32_dpp v189, v23 row_shr:1 row_mask:0xf bank_mask:0xf
	v_mov_b32_dpp v187, v87 row_shr:2 row_mask:0xf bank_mask:0xf
	v_mov_b32_dpp v185, v87 row_shr:1 row_mask:0xf bank_mask:0xf
	v_add_u32_e32 v207, 0x90, v172
	s_cmp_lg_u32 s42, 64
	s_cselect_b64 vcc, -1, s[40:41]
	s_and_saveexec_b64 s[0:1], vcc
	s_cbranch_execz .LBB0_615
	s_nop 0
	v_pk_fma_f32 v[198:199], v[146:147], v[198:199], v[158:159]
	v_pk_fma_f32 v[190:191], v[148:149], v[190:191], v[160:161]
	v_pk_fma_f32 v[196:197], v[150:151], v[196:197], v[198:199]
	v_pk_fma_f32 v[188:189], v[152:153], v[188:189], v[190:191]
	v_pk_fma_f32 v[196:197], v[20:21], v[154:155], v[196:197]
	v_pk_fma_f32 v[188:189], v[22:23], v[156:157], v[188:189]
	v_pk_fma_f32 v[194:195], v[130:131], v[194:195], v[142:143]
	v_pk_fma_f32 v[192:193], v[134:135], v[192:193], v[194:195]
	v_pk_mul_f32 v[210:211], v[196:197], v[196:197]
	v_pk_fma_f32 v[210:211], v[210:211], v[214:215], v[216:217]
	v_pk_mul_f32 v[210:211], v[210:211], v[196:197]
	v_exp_f32_e32 v210, v210
	v_exp_f32_e32 v211, v211
	s_nop 1
	v_pk_add_f32 v[210:211], v[210:211], v[218:219]
	v_rcp_f32_e32 v198, v210
	v_rcp_f32_e32 v199, v211
	s_nop 1
	v_pk_fma_f32 v[194:195], v[196:197], v[198:199], v[196:197] neg_lo:[1,0,0] neg_hi:[1,0,0]
	v_pk_fma_f32 v[192:193], v[84:85], v[138:139], v[192:193]
	v_pk_fma_f32 v[186:187], v[132:133], v[186:187], v[144:145]
	v_pk_mul_f32 v[190:191], v[192:193], v[194:195]
	v_pk_fma_f32 v[184:185], v[136:137], v[184:185], v[186:187]
	v_pk_mul_f32 v[210:211], v[188:189], v[188:189]
	v_pk_fma_f32 v[210:211], v[210:211], v[214:215], v[216:217]
	v_pk_mul_f32 v[210:211], v[210:211], v[188:189]
	v_exp_f32_e32 v210, v210
	v_exp_f32_e32 v211, v211
	s_nop 1
	v_pk_add_f32 v[210:211], v[210:211], v[218:219]
	v_rcp_f32_e32 v192, v210
	v_rcp_f32_e32 v193, v211
	s_nop 1
	v_pk_fma_f32 v[186:187], v[188:189], v[192:193], v[188:189] neg_lo:[1,0,0] neg_hi:[1,0,0]
	v_pk_fma_f32 v[184:185], v[86:87], v[140:141], v[184:185]
	s_nop 0
	v_pk_mul_f32 v[184:185], v[184:185], v[186:187]
	v_cvt_pk_bf16_f32 v186, v190, v191
	v_cvt_pk_bf16_f32 v187, v184, v185
	v_mad_i64_i32 v[184:185], s[6:7], v207, s5, v[178:179]
	global_store_dwordx2 v[184:185], v[186:187], off
.LBB0_615:
	s_or_b64 exec, exec, s[0:1]
	s_cmp_lg_u32 s42, 64
	s_cselect_b64 exec, -1, 0
	s_nop 1
	v_mov_b32_dpp v198, v20 row_ror:2 row_mask:0xf bank_mask:0x1
	v_mov_b32_dpp v196, v20 row_ror:1 row_mask:0xf bank_mask:0x1
	v_mov_b32_dpp v194, v84 row_ror:2 row_mask:0xf bank_mask:0x1
	v_mov_b32_dpp v192, v84 row_ror:1 row_mask:0xf bank_mask:0x1
	v_mov_b32_dpp v199, v21 row_ror:2 row_mask:0xf bank_mask:0x1
	v_mov_b32_dpp v197, v21 row_ror:1 row_mask:0xf bank_mask:0x1
	v_mov_b32_dpp v195, v85 row_ror:2 row_mask:0xf bank_mask:0x1
	v_mov_b32_dpp v193, v85 row_ror:1 row_mask:0xf bank_mask:0x1
	v_mov_b32_dpp v190, v22 row_ror:2 row_mask:0xf bank_mask:0x1
	v_mov_b32_dpp v188, v22 row_ror:1 row_mask:0xf bank_mask:0x1
	v_mov_b32_dpp v186, v86 row_ror:2 row_mask:0xf bank_mask:0x1
	v_mov_b32_dpp v184, v86 row_ror:1 row_mask:0xf bank_mask:0x1
	v_mov_b32_dpp v191, v23 row_ror:2 row_mask:0xf bank_mask:0x1
	v_mov_b32_dpp v189, v23 row_ror:1 row_mask:0xf bank_mask:0x1
	v_mov_b32_dpp v187, v87 row_ror:2 row_mask:0xf bank_mask:0x1
	v_mov_b32_dpp v185, v87 row_ror:1 row_mask:0xf bank_mask:0x1
	s_mov_b64 exec, -1
	s_nop 1
	v_mov_b32_dpp v198, v12 row_shr:2 row_mask:0xf bank_mask:0xf
	v_mov_b32_dpp v196, v12 row_shr:1 row_mask:0xf bank_mask:0xf
	v_mov_b32_dpp v194, v76 row_shr:2 row_mask:0xf bank_mask:0xf
	v_mov_b32_dpp v192, v76 row_shr:1 row_mask:0xf bank_mask:0xf
	v_mov_b32_dpp v199, v13 row_shr:2 row_mask:0xf bank_mask:0xf
	v_mov_b32_dpp v197, v13 row_shr:1 row_mask:0xf bank_mask:0xf
	v_mov_b32_dpp v195, v77 row_shr:2 row_mask:0xf bank_mask:0xf
	v_mov_b32_dpp v193, v77 row_shr:1 row_mask:0xf bank_mask:0xf
	v_mov_b32_dpp v190, v14 row_shr:2 row_mask:0xf bank_mask:0xf
	v_mov_b32_dpp v188, v14 row_shr:1 row_mask:0xf bank_mask:0xf
	v_mov_b32_dpp v186, v78 row_shr:2 row_mask:0xf bank_mask:0xf
	v_mov_b32_dpp v184, v78 row_shr:1 row_mask:0xf bank_mask:0xf
	v_mov_b32_dpp v191, v15 row_shr:2 row_mask:0xf bank_mask:0xf
	v_mov_b32_dpp v189, v15 row_shr:1 row_mask:0xf bank_mask:0xf
	v_mov_b32_dpp v187, v79 row_shr:2 row_mask:0xf bank_mask:0xf
	v_mov_b32_dpp v185, v79 row_shr:1 row_mask:0xf bank_mask:0xf
	v_add_u32_e32 v208, 0xa0, v172
	s_cmp_lg_u32 s42, 64
	s_cselect_b64 vcc, -1, s[40:41]
	s_and_saveexec_b64 s[0:1], vcc
	s_cbranch_execz .LBB0_617
	s_nop 0
	v_pk_fma_f32 v[198:199], v[146:147], v[198:199], v[158:159]
	v_pk_fma_f32 v[190:191], v[148:149], v[190:191], v[160:161]
	v_pk_fma_f32 v[196:197], v[150:151], v[196:197], v[198:199]
	v_pk_fma_f32 v[188:189], v[152:153], v[188:189], v[190:191]
	v_pk_fma_f32 v[196:197], v[12:13], v[154:155], v[196:197]
	v_pk_fma_f32 v[188:189], v[14:15], v[156:157], v[188:189]
	v_pk_fma_f32 v[194:195], v[130:131], v[194:195], v[142:143]
	v_pk_fma_f32 v[192:193], v[134:135], v[192:193], v[194:195]
	v_pk_mul_f32 v[210:211], v[196:197], v[196:197]
	v_pk_fma_f32 v[210:211], v[210:211], v[214:215], v[216:217]
	v_pk_mul_f32 v[210:211], v[210:211], v[196:197]
	v_exp_f32_e32 v210, v210
	v_exp_f32_e32 v211, v211
	s_nop 1
	v_pk_add_f32 v[210:211], v[210:211], v[218:219]
	v_rcp_f32_e32 v198, v210
	v_rcp_f32_e32 v199, v211
	s_nop 1
	v_pk_fma_f32 v[194:195], v[196:197], v[198:199], v[196:197] neg_lo:[1,0,0] neg_hi:[1,0,0]
	v_pk_fma_f32 v[192:193], v[76:77], v[138:139], v[192:193]
	v_pk_fma_f32 v[186:187], v[132:133], v[186:187], v[144:145]
	v_pk_mul_f32 v[190:191], v[192:193], v[194:195]
	v_pk_fma_f32 v[184:185], v[136:137], v[184:185], v[186:187]
	v_pk_mul_f32 v[210:211], v[188:189], v[188:189]
	v_pk_fma_f32 v[210:211], v[210:211], v[214:215], v[216:217]
	v_pk_mul_f32 v[210:211], v[210:211], v[188:189]
	v_exp_f32_e32 v210, v210
	v_exp_f32_e32 v211, v211
	s_nop 1
	v_pk_add_f32 v[210:211], v[210:211], v[218:219]
	v_rcp_f32_e32 v192, v210
	v_rcp_f32_e32 v193, v211
	s_nop 1
	v_pk_fma_f32 v[186:187], v[188:189], v[192:193], v[188:189] neg_lo:[1,0,0] neg_hi:[1,0,0]
	v_pk_fma_f32 v[184:185], v[78:79], v[140:141], v[184:185]
	s_nop 0
	v_pk_mul_f32 v[184:185], v[184:185], v[186:187]
	v_cvt_pk_bf16_f32 v186, v190, v191
	v_cvt_pk_bf16_f32 v187, v184, v185
	v_mad_i64_i32 v[184:185], s[6:7], v208, s5, v[178:179]
	global_store_dwordx2 v[184:185], v[186:187], off
.LBB0_617:
	s_or_b64 exec, exec, s[0:1]
	s_cmp_lg_u32 s42, 64
	s_cselect_b64 exec, -1, 0
	s_nop 1
	v_mov_b32_dpp v198, v12 row_ror:2 row_mask:0xf bank_mask:0x1
	v_mov_b32_dpp v196, v12 row_ror:1 row_mask:0xf bank_mask:0x1
	v_mov_b32_dpp v194, v76 row_ror:2 row_mask:0xf bank_mask:0x1
	v_mov_b32_dpp v192, v76 row_ror:1 row_mask:0xf bank_mask:0x1
	v_mov_b32_dpp v199, v13 row_ror:2 row_mask:0xf bank_mask:0x1
	v_mov_b32_dpp v197, v13 row_ror:1 row_mask:0xf bank_mask:0x1
	v_mov_b32_dpp v195, v77 row_ror:2 row_mask:0xf bank_mask:0x1
	v_mov_b32_dpp v193, v77 row_ror:1 row_mask:0xf bank_mask:0x1
	v_mov_b32_dpp v190, v14 row_ror:2 row_mask:0xf bank_mask:0x1
	v_mov_b32_dpp v188, v14 row_ror:1 row_mask:0xf bank_mask:0x1
	v_mov_b32_dpp v186, v78 row_ror:2 row_mask:0xf bank_mask:0x1
	v_mov_b32_dpp v184, v78 row_ror:1 row_mask:0xf bank_mask:0x1
	v_mov_b32_dpp v191, v15 row_ror:2 row_mask:0xf bank_mask:0x1
	v_mov_b32_dpp v189, v15 row_ror:1 row_mask:0xf bank_mask:0x1
	v_mov_b32_dpp v187, v79 row_ror:2 row_mask:0xf bank_mask:0x1
	v_mov_b32_dpp v185, v79 row_ror:1 row_mask:0xf bank_mask:0x1
	s_mov_b64 exec, -1
	s_nop 1
	v_mov_b32_dpp v198, v4 row_shr:2 row_mask:0xf bank_mask:0xf
	v_mov_b32_dpp v196, v4 row_shr:1 row_mask:0xf bank_mask:0xf
	v_mov_b32_dpp v194, v64 row_shr:2 row_mask:0xf bank_mask:0xf
	v_mov_b32_dpp v192, v64 row_shr:1 row_mask:0xf bank_mask:0xf
	v_mov_b32_dpp v199, v5 row_shr:2 row_mask:0xf bank_mask:0xf
	v_mov_b32_dpp v197, v5 row_shr:1 row_mask:0xf bank_mask:0xf
	v_mov_b32_dpp v195, v65 row_shr:2 row_mask:0xf bank_mask:0xf
	v_mov_b32_dpp v193, v65 row_shr:1 row_mask:0xf bank_mask:0xf
	v_mov_b32_dpp v190, v6 row_shr:2 row_mask:0xf bank_mask:0xf
	v_mov_b32_dpp v188, v6 row_shr:1 row_mask:0xf bank_mask:0xf
	v_mov_b32_dpp v186, v66 row_shr:2 row_mask:0xf bank_mask:0xf
	v_mov_b32_dpp v184, v66 row_shr:1 row_mask:0xf bank_mask:0xf
	v_mov_b32_dpp v191, v7 row_shr:2 row_mask:0xf bank_mask:0xf
	v_mov_b32_dpp v189, v7 row_shr:1 row_mask:0xf bank_mask:0xf
	v_mov_b32_dpp v187, v67 row_shr:2 row_mask:0xf bank_mask:0xf
	v_mov_b32_dpp v185, v67 row_shr:1 row_mask:0xf bank_mask:0xf
	v_add_u32_e32 v209, 0xb0, v172
	s_cmp_lg_u32 s42, 64
	s_cselect_b64 vcc, -1, s[40:41]
	s_and_saveexec_b64 s[0:1], vcc
	s_cbranch_execz .LBB0_619
	s_nop 0
	v_pk_fma_f32 v[146:147], v[146:147], v[198:199], v[158:159]
	v_pk_fma_f32 v[130:131], v[130:131], v[194:195], v[142:143]
	v_pk_fma_f32 v[146:147], v[150:151], v[196:197], v[146:147]
	v_pk_fma_f32 v[130:131], v[134:135], v[192:193], v[130:131]
	v_pk_fma_f32 v[146:147], v[4:5], v[154:155], v[146:147]
	v_pk_fma_f32 v[130:131], v[64:65], v[138:139], v[130:131]
	v_pk_fma_f32 v[138:139], v[148:149], v[190:191], v[160:161]
	v_pk_fma_f32 v[132:133], v[132:133], v[186:187], v[144:145]
	v_pk_fma_f32 v[138:139], v[152:153], v[188:189], v[138:139]
	v_pk_fma_f32 v[138:139], v[6:7], v[156:157], v[138:139]
	v_pk_mul_f32 v[210:211], v[146:147], v[146:147]
	v_pk_fma_f32 v[210:211], v[210:211], v[214:215], v[216:217]
	v_pk_mul_f32 v[210:211], v[210:211], v[146:147]
	v_exp_f32_e32 v210, v210
	v_exp_f32_e32 v211, v211
	s_nop 1
	v_pk_add_f32 v[210:211], v[210:211], v[218:219]
	v_rcp_f32_e32 v150, v210
	v_rcp_f32_e32 v151, v211
	s_nop 1
	v_pk_fma_f32 v[134:135], v[146:147], v[150:151], v[146:147] neg_lo:[1,0,0] neg_hi:[1,0,0]
	v_pk_fma_f32 v[132:133], v[136:137], v[184:185], v[132:133]
	v_pk_mul_f32 v[130:131], v[130:131], v[134:135]
	v_pk_fma_f32 v[132:133], v[66:67], v[140:141], v[132:133]
	v_cvt_pk_bf16_f32 v130, v130, v131
	v_pk_mul_f32 v[210:211], v[138:139], v[138:139]
	v_pk_fma_f32 v[210:211], v[210:211], v[214:215], v[216:217]
	v_pk_mul_f32 v[210:211], v[210:211], v[138:139]
	v_exp_f32_e32 v210, v210
	v_exp_f32_e32 v211, v211
	s_nop 1
	v_pk_add_f32 v[210:211], v[210:211], v[218:219]
	v_rcp_f32_e32 v134, v210
	v_rcp_f32_e32 v135, v211
	s_nop 1
	v_pk_fma_f32 v[134:135], v[138:139], v[134:135], v[138:139] neg_lo:[1,0,0] neg_hi:[1,0,0]
	s_nop 0
	v_pk_mul_f32 v[132:133], v[132:133], v[134:135]
	s_nop 0
	v_cvt_pk_bf16_f32 v131, v132, v133
	v_mad_i64_i32 v[132:133], s[6:7], v209, s5, v[178:179]
	global_store_dwordx2 v[132:133], v[130:131], off
.LBB0_619:
	s_or_b64 exec, exec, s[0:1]
	s_waitcnt vmcnt(0)
	v_or_b32_e32 v130, 4, v176
	v_ashrrev_i32_e32 v131, 31, v130
	v_readlane_b32 s0, v254, 21
	v_lshlrev_b64 v[142:143], 2, v[130:131]
	v_readlane_b32 s1, v254, 22
	global_load_dwordx4 v[146:149], v[180:181], off offset:16
	v_lshl_add_u64 v[132:133], s[68:69], 0, v[142:143]
	v_lshl_add_u64 v[130:131], s[0:1], 0, v[142:143]
	global_load_dwordx4 v[150:153], v[130:131], off
	global_load_dwordx4 v[154:157], v[132:133], off
	global_load_dwordx4 v[158:161], v[182:183], off offset:16
	v_lshl_add_u64 v[130:131], s[70:71], 0, v[142:143]
	v_lshl_add_u64 v[134:135], s[72:73], 0, v[142:143]
	v_lshl_add_u64 v[138:139], s[74:75], 0, v[142:143]
	v_lshl_add_u64 v[142:143], s[76:77], 0, v[142:143]
	global_load_dwordx4 v[130:133], v[130:131], off
	s_nop 0
	global_load_dwordx4 v[134:137], v[134:135], off
	v_mov_b32_dpp v194, v56 row_shr:2 row_mask:0xf bank_mask:0xf bound_ctrl:1
	global_load_dwordx4 v[138:141], v[138:139], off
	v_mov_b32_dpp v192, v56 row_shr:1 row_mask:0xf bank_mask:0xf bound_ctrl:1
	global_load_dwordx4 v[142:145], v[142:143], off
	v_mov_b32_dpp v190, v122 row_shr:2 row_mask:0xf bank_mask:0xf bound_ctrl:1
	v_mov_b32_dpp v188, v122 row_shr:1 row_mask:0xf bank_mask:0xf bound_ctrl:1
	v_mov_b32_dpp v195, v57 row_shr:2 row_mask:0xf bank_mask:0xf bound_ctrl:1
	v_mov_b32_dpp v193, v57 row_shr:1 row_mask:0xf bank_mask:0xf bound_ctrl:1
	v_mov_b32_dpp v191, v123 row_shr:2 row_mask:0xf bank_mask:0xf bound_ctrl:1
	v_mov_b32_dpp v189, v123 row_shr:1 row_mask:0xf bank_mask:0xf bound_ctrl:1
	v_mov_b32_dpp v186, v58 row_shr:2 row_mask:0xf bank_mask:0xf bound_ctrl:1
	v_mov_b32_dpp v184, v58 row_shr:1 row_mask:0xf bank_mask:0xf bound_ctrl:1
	v_mov_b32_dpp v182, v124 row_shr:2 row_mask:0xf bank_mask:0xf bound_ctrl:1
	v_mov_b32_dpp v180, v124 row_shr:1 row_mask:0xf bank_mask:0xf bound_ctrl:1
	v_mov_b32_dpp v187, v59 row_shr:2 row_mask:0xf bank_mask:0xf bound_ctrl:1
	v_mov_b32_dpp v185, v59 row_shr:1 row_mask:0xf bank_mask:0xf bound_ctrl:1
	v_mov_b32_dpp v183, v125 row_shr:2 row_mask:0xf bank_mask:0xf bound_ctrl:1
	v_mov_b32_dpp v181, v125 row_shr:1 row_mask:0xf bank_mask:0xf bound_ctrl:1
	s_and_saveexec_b64 s[0:1], s[40:41]
	s_cbranch_execz .LBB0_621
	s_waitcnt vmcnt(4)
	v_pk_fma_f32 v[194:195], v[146:147], v[194:195], v[158:159]
	v_pk_fma_f32 v[186:187], v[148:149], v[186:187], v[160:161]
	v_pk_fma_f32 v[192:193], v[150:151], v[192:193], v[194:195]
	v_pk_fma_f32 v[184:185], v[152:153], v[184:185], v[186:187]
	v_pk_fma_f32 v[192:193], v[56:57], v[154:155], v[192:193]
	v_pk_fma_f32 v[184:185], v[58:59], v[156:157], v[184:185]
	s_waitcnt vmcnt(0)
	v_pk_fma_f32 v[190:191], v[130:131], v[190:191], v[142:143]
	v_pk_fma_f32 v[188:189], v[134:135], v[188:189], v[190:191]
	v_pk_mul_f32 v[210:211], v[192:193], v[192:193]
	v_pk_fma_f32 v[210:211], v[210:211], v[214:215], v[216:217]
	v_pk_mul_f32 v[210:211], v[210:211], v[192:193]
	v_exp_f32_e32 v210, v210
	v_exp_f32_e32 v211, v211
	s_nop 1
	v_pk_add_f32 v[210:211], v[210:211], v[218:219]
	v_rcp_f32_e32 v194, v210
	v_rcp_f32_e32 v195, v211
	s_nop 1
	v_pk_fma_f32 v[190:191], v[192:193], v[194:195], v[192:193] neg_lo:[1,0,0] neg_hi:[1,0,0]
	v_pk_fma_f32 v[188:189], v[122:123], v[138:139], v[188:189]
	v_pk_fma_f32 v[182:183], v[132:133], v[182:183], v[144:145]
	v_pk_mul_f32 v[186:187], v[188:189], v[190:191]
	v_pk_fma_f32 v[180:181], v[136:137], v[180:181], v[182:183]
	v_pk_mul_f32 v[210:211], v[184:185], v[184:185]
	v_pk_fma_f32 v[210:211], v[210:211], v[214:215], v[216:217]
	v_pk_mul_f32 v[210:211], v[210:211], v[184:185]
	v_exp_f32_e32 v210, v210
	v_exp_f32_e32 v211, v211
	s_nop 1
	v_pk_add_f32 v[210:211], v[210:211], v[218:219]
	v_rcp_f32_e32 v188, v210
	v_rcp_f32_e32 v189, v211
	s_nop 1
	v_pk_fma_f32 v[182:183], v[184:185], v[188:189], v[184:185] neg_lo:[1,0,0] neg_hi:[1,0,0]
	v_pk_fma_f32 v[180:181], v[124:125], v[140:141], v[180:181]
	s_nop 0
	v_pk_mul_f32 v[180:181], v[180:181], v[182:183]
	v_cvt_pk_bf16_f32 v182, v186, v187
	v_cvt_pk_bf16_f32 v183, v180, v181
	v_mad_i64_i32 v[180:181], s[6:7], v172, s5, v[178:179]
	global_store_dwordx2 v[180:181], v[182:183], off offset:8
.LBB0_621:
	s_or_b64 exec, exec, s[0:1]
	s_cmp_lg_u32 s42, 64
	s_cselect_b64 exec, -1, 0
	s_nop 1
	v_mov_b32_dpp v194, v56 row_ror:2 row_mask:0xf bank_mask:0x1
	v_mov_b32_dpp v192, v56 row_ror:1 row_mask:0xf bank_mask:0x1
	v_mov_b32_dpp v190, v122 row_ror:2 row_mask:0xf bank_mask:0x1
	v_mov_b32_dpp v188, v122 row_ror:1 row_mask:0xf bank_mask:0x1
	v_mov_b32_dpp v195, v57 row_ror:2 row_mask:0xf bank_mask:0x1
	v_mov_b32_dpp v193, v57 row_ror:1 row_mask:0xf bank_mask:0x1
	v_mov_b32_dpp v191, v123 row_ror:2 row_mask:0xf bank_mask:0x1
	v_mov_b32_dpp v189, v123 row_ror:1 row_mask:0xf bank_mask:0x1
	v_mov_b32_dpp v186, v58 row_ror:2 row_mask:0xf bank_mask:0x1
	v_mov_b32_dpp v184, v58 row_ror:1 row_mask:0xf bank_mask:0x1
	v_mov_b32_dpp v182, v124 row_ror:2 row_mask:0xf bank_mask:0x1
	v_mov_b32_dpp v180, v124 row_ror:1 row_mask:0xf bank_mask:0x1
	v_mov_b32_dpp v187, v59 row_ror:2 row_mask:0xf bank_mask:0x1
	v_mov_b32_dpp v185, v59 row_ror:1 row_mask:0xf bank_mask:0x1
	v_mov_b32_dpp v183, v125 row_ror:2 row_mask:0xf bank_mask:0x1
	v_mov_b32_dpp v181, v125 row_ror:1 row_mask:0xf bank_mask:0x1
	s_mov_b64 exec, -1
	s_nop 1
	v_mov_b32_dpp v194, v48 row_shr:2 row_mask:0xf bank_mask:0xf
	v_mov_b32_dpp v192, v48 row_shr:1 row_mask:0xf bank_mask:0xf
	v_mov_b32_dpp v190, v114 row_shr:2 row_mask:0xf bank_mask:0xf
	v_mov_b32_dpp v188, v114 row_shr:1 row_mask:0xf bank_mask:0xf
	v_mov_b32_dpp v195, v49 row_shr:2 row_mask:0xf bank_mask:0xf
	v_mov_b32_dpp v193, v49 row_shr:1 row_mask:0xf bank_mask:0xf
	v_mov_b32_dpp v191, v115 row_shr:2 row_mask:0xf bank_mask:0xf
	v_mov_b32_dpp v189, v115 row_shr:1 row_mask:0xf bank_mask:0xf
	v_mov_b32_dpp v186, v50 row_shr:2 row_mask:0xf bank_mask:0xf
	v_mov_b32_dpp v184, v50 row_shr:1 row_mask:0xf bank_mask:0xf
	v_mov_b32_dpp v182, v116 row_shr:2 row_mask:0xf bank_mask:0xf
	v_mov_b32_dpp v180, v116 row_shr:1 row_mask:0xf bank_mask:0xf
	v_mov_b32_dpp v187, v51 row_shr:2 row_mask:0xf bank_mask:0xf
	v_mov_b32_dpp v185, v51 row_shr:1 row_mask:0xf bank_mask:0xf
	v_mov_b32_dpp v183, v117 row_shr:2 row_mask:0xf bank_mask:0xf
	v_mov_b32_dpp v181, v117 row_shr:1 row_mask:0xf bank_mask:0xf
	s_cmp_lg_u32 s42, 64
	s_cselect_b64 vcc, -1, s[40:41]
	s_and_saveexec_b64 s[0:1], vcc
	s_cbranch_execz .LBB0_623
	s_nop 0
	v_pk_fma_f32 v[194:195], v[146:147], v[194:195], v[158:159]
	v_pk_fma_f32 v[186:187], v[148:149], v[186:187], v[160:161]
	v_pk_fma_f32 v[192:193], v[150:151], v[192:193], v[194:195]
	v_pk_fma_f32 v[184:185], v[152:153], v[184:185], v[186:187]
	v_pk_fma_f32 v[192:193], v[48:49], v[154:155], v[192:193]
	v_pk_fma_f32 v[184:185], v[50:51], v[156:157], v[184:185]
	s_nop 0
	v_pk_fma_f32 v[190:191], v[130:131], v[190:191], v[142:143]
	v_pk_fma_f32 v[188:189], v[134:135], v[188:189], v[190:191]
	v_pk_mul_f32 v[210:211], v[192:193], v[192:193]
	v_pk_fma_f32 v[210:211], v[210:211], v[214:215], v[216:217]
	v_pk_mul_f32 v[210:211], v[210:211], v[192:193]
	v_exp_f32_e32 v210, v210
	v_exp_f32_e32 v211, v211
	s_nop 1
	v_pk_add_f32 v[210:211], v[210:211], v[218:219]
	v_rcp_f32_e32 v194, v210
	v_rcp_f32_e32 v195, v211
	s_nop 1
	v_pk_fma_f32 v[190:191], v[192:193], v[194:195], v[192:193] neg_lo:[1,0,0] neg_hi:[1,0,0]
	v_pk_fma_f32 v[188:189], v[114:115], v[138:139], v[188:189]
	v_pk_fma_f32 v[182:183], v[132:133], v[182:183], v[144:145]
	v_pk_mul_f32 v[186:187], v[188:189], v[190:191]
	v_pk_fma_f32 v[180:181], v[136:137], v[180:181], v[182:183]
	v_pk_mul_f32 v[210:211], v[184:185], v[184:185]
	v_pk_fma_f32 v[210:211], v[210:211], v[214:215], v[216:217]
	v_pk_mul_f32 v[210:211], v[210:211], v[184:185]
	v_exp_f32_e32 v210, v210
	v_exp_f32_e32 v211, v211
	s_nop 1
	v_pk_add_f32 v[210:211], v[210:211], v[218:219]
	v_rcp_f32_e32 v188, v210
	v_rcp_f32_e32 v189, v211
	s_nop 1
	v_pk_fma_f32 v[182:183], v[184:185], v[188:189], v[184:185] neg_lo:[1,0,0] neg_hi:[1,0,0]
	v_pk_fma_f32 v[180:181], v[116:117], v[140:141], v[180:181]
	s_nop 0
	v_pk_mul_f32 v[180:181], v[180:181], v[182:183]
	v_cvt_pk_bf16_f32 v182, v186, v187
	v_cvt_pk_bf16_f32 v183, v180, v181
	v_mad_i64_i32 v[180:181], s[6:7], v175, s5, v[178:179]
	global_store_dwordx2 v[180:181], v[182:183], off offset:8
.LBB0_623:
	s_or_b64 exec, exec, s[0:1]
	s_cmp_lg_u32 s42, 64
	s_cselect_b64 exec, -1, 0
	s_nop 1
	v_mov_b32_dpp v194, v48 row_ror:2 row_mask:0xf bank_mask:0x1
	v_mov_b32_dpp v192, v48 row_ror:1 row_mask:0xf bank_mask:0x1
	v_mov_b32_dpp v190, v114 row_ror:2 row_mask:0xf bank_mask:0x1
	v_mov_b32_dpp v188, v114 row_ror:1 row_mask:0xf bank_mask:0x1
	v_mov_b32_dpp v195, v49 row_ror:2 row_mask:0xf bank_mask:0x1
	v_mov_b32_dpp v193, v49 row_ror:1 row_mask:0xf bank_mask:0x1
	v_mov_b32_dpp v191, v115 row_ror:2 row_mask:0xf bank_mask:0x1
	v_mov_b32_dpp v189, v115 row_ror:1 row_mask:0xf bank_mask:0x1
	v_mov_b32_dpp v186, v50 row_ror:2 row_mask:0xf bank_mask:0x1
	v_mov_b32_dpp v184, v50 row_ror:1 row_mask:0xf bank_mask:0x1
	v_mov_b32_dpp v182, v116 row_ror:2 row_mask:0xf bank_mask:0x1
	v_mov_b32_dpp v180, v116 row_ror:1 row_mask:0xf bank_mask:0x1
	v_mov_b32_dpp v187, v51 row_ror:2 row_mask:0xf bank_mask:0x1
	v_mov_b32_dpp v185, v51 row_ror:1 row_mask:0xf bank_mask:0x1
	v_mov_b32_dpp v183, v117 row_ror:2 row_mask:0xf bank_mask:0x1
	v_mov_b32_dpp v181, v117 row_ror:1 row_mask:0xf bank_mask:0x1
	s_mov_b64 exec, -1
	s_nop 1
	v_mov_b32_dpp v194, v40 row_shr:2 row_mask:0xf bank_mask:0xf
	v_mov_b32_dpp v192, v40 row_shr:1 row_mask:0xf bank_mask:0xf
	v_mov_b32_dpp v190, v104 row_shr:2 row_mask:0xf bank_mask:0xf
	v_mov_b32_dpp v188, v104 row_shr:1 row_mask:0xf bank_mask:0xf
	v_mov_b32_dpp v195, v41 row_shr:2 row_mask:0xf bank_mask:0xf
	v_mov_b32_dpp v193, v41 row_shr:1 row_mask:0xf bank_mask:0xf
	v_mov_b32_dpp v191, v105 row_shr:2 row_mask:0xf bank_mask:0xf
	v_mov_b32_dpp v189, v105 row_shr:1 row_mask:0xf bank_mask:0xf
	v_mov_b32_dpp v186, v42 row_shr:2 row_mask:0xf bank_mask:0xf
	v_mov_b32_dpp v184, v42 row_shr:1 row_mask:0xf bank_mask:0xf
	v_mov_b32_dpp v182, v106 row_shr:2 row_mask:0xf bank_mask:0xf
	v_mov_b32_dpp v180, v106 row_shr:1 row_mask:0xf bank_mask:0xf
	v_mov_b32_dpp v187, v43 row_shr:2 row_mask:0xf bank_mask:0xf
	v_mov_b32_dpp v185, v43 row_shr:1 row_mask:0xf bank_mask:0xf
	v_mov_b32_dpp v183, v107 row_shr:2 row_mask:0xf bank_mask:0xf
	v_mov_b32_dpp v181, v107 row_shr:1 row_mask:0xf bank_mask:0xf
	s_cmp_lg_u32 s42, 64
	s_cselect_b64 vcc, -1, s[40:41]
	s_and_saveexec_b64 s[0:1], vcc
	s_cbranch_execz .LBB0_625
	s_nop 0
	v_pk_fma_f32 v[194:195], v[146:147], v[194:195], v[158:159]
	v_pk_fma_f32 v[186:187], v[148:149], v[186:187], v[160:161]
	v_pk_fma_f32 v[192:193], v[150:151], v[192:193], v[194:195]
	v_pk_fma_f32 v[184:185], v[152:153], v[184:185], v[186:187]
	v_pk_fma_f32 v[192:193], v[40:41], v[154:155], v[192:193]
	v_pk_fma_f32 v[184:185], v[42:43], v[156:157], v[184:185]
	s_nop 0
	v_pk_fma_f32 v[190:191], v[130:131], v[190:191], v[142:143]
	v_pk_fma_f32 v[188:189], v[134:135], v[188:189], v[190:191]
	v_pk_mul_f32 v[210:211], v[192:193], v[192:193]
	v_pk_fma_f32 v[210:211], v[210:211], v[214:215], v[216:217]
	v_pk_mul_f32 v[210:211], v[210:211], v[192:193]
	v_exp_f32_e32 v210, v210
	v_exp_f32_e32 v211, v211
	s_nop 1
	v_pk_add_f32 v[210:211], v[210:211], v[218:219]
	v_rcp_f32_e32 v194, v210
	v_rcp_f32_e32 v195, v211
	s_nop 1
	v_pk_fma_f32 v[190:191], v[192:193], v[194:195], v[192:193] neg_lo:[1,0,0] neg_hi:[1,0,0]
	v_pk_fma_f32 v[188:189], v[104:105], v[138:139], v[188:189]
	v_pk_mul_f32 v[186:187], v[188:189], v[190:191]
	v_pk_fma_f32 v[182:183], v[132:133], v[182:183], v[144:145]
	s_nop 0
	v_pk_fma_f32 v[180:181], v[136:137], v[180:181], v[182:183]
	v_pk_mul_f32 v[210:211], v[184:185], v[184:185]
	v_pk_fma_f32 v[210:211], v[210:211], v[214:215], v[216:217]
	v_pk_mul_f32 v[210:211], v[210:211], v[184:185]
	v_exp_f32_e32 v210, v210
	v_exp_f32_e32 v211, v211
	s_nop 1
	v_pk_add_f32 v[210:211], v[210:211], v[218:219]
	v_rcp_f32_e32 v188, v210
	v_rcp_f32_e32 v189, v211
	s_nop 1
	v_pk_fma_f32 v[182:183], v[184:185], v[188:189], v[184:185] neg_lo:[1,0,0] neg_hi:[1,0,0]
	v_pk_fma_f32 v[180:181], v[106:107], v[140:141], v[180:181]
	s_nop 0
	v_pk_mul_f32 v[180:181], v[180:181], v[182:183]
	v_cvt_pk_bf16_f32 v182, v186, v187
	v_cvt_pk_bf16_f32 v183, v180, v181
	v_mad_i64_i32 v[180:181], s[6:7], v205, s5, v[178:179]
	global_store_dwordx2 v[180:181], v[182:183], off offset:8
.LBB0_625:
	s_or_b64 exec, exec, s[0:1]
	s_cmp_lg_u32 s42, 64
	s_cselect_b64 exec, -1, 0
	s_nop 1
	v_mov_b32_dpp v194, v40 row_ror:2 row_mask:0xf bank_mask:0x1
	v_mov_b32_dpp v192, v40 row_ror:1 row_mask:0xf bank_mask:0x1
	v_mov_b32_dpp v190, v104 row_ror:2 row_mask:0xf bank_mask:0x1
	v_mov_b32_dpp v188, v104 row_ror:1 row_mask:0xf bank_mask:0x1
	v_mov_b32_dpp v195, v41 row_ror:2 row_mask:0xf bank_mask:0x1
	v_mov_b32_dpp v193, v41 row_ror:1 row_mask:0xf bank_mask:0x1
	v_mov_b32_dpp v191, v105 row_ror:2 row_mask:0xf bank_mask:0x1
	v_mov_b32_dpp v189, v105 row_ror:1 row_mask:0xf bank_mask:0x1
	v_mov_b32_dpp v186, v42 row_ror:2 row_mask:0xf bank_mask:0x1
	v_mov_b32_dpp v184, v42 row_ror:1 row_mask:0xf bank_mask:0x1
	v_mov_b32_dpp v182, v106 row_ror:2 row_mask:0xf bank_mask:0x1
	v_mov_b32_dpp v180, v106 row_ror:1 row_mask:0xf bank_mask:0x1
	v_mov_b32_dpp v187, v43 row_ror:2 row_mask:0xf bank_mask:0x1
	v_mov_b32_dpp v185, v43 row_ror:1 row_mask:0xf bank_mask:0x1
	v_mov_b32_dpp v183, v107 row_ror:2 row_mask:0xf bank_mask:0x1
	v_mov_b32_dpp v181, v107 row_ror:1 row_mask:0xf bank_mask:0x1
	s_mov_b64 exec, -1
	s_nop 1
	v_mov_b32_dpp v194, v32 row_shr:2 row_mask:0xf bank_mask:0xf
	v_mov_b32_dpp v192, v32 row_shr:1 row_mask:0xf bank_mask:0xf
	v_mov_b32_dpp v190, v96 row_shr:2 row_mask:0xf bank_mask:0xf
	v_mov_b32_dpp v188, v96 row_shr:1 row_mask:0xf bank_mask:0xf
	v_mov_b32_dpp v195, v33 row_shr:2 row_mask:0xf bank_mask:0xf
	v_mov_b32_dpp v193, v33 row_shr:1 row_mask:0xf bank_mask:0xf
	v_mov_b32_dpp v191, v97 row_shr:2 row_mask:0xf bank_mask:0xf
	v_mov_b32_dpp v189, v97 row_shr:1 row_mask:0xf bank_mask:0xf
	v_mov_b32_dpp v186, v34 row_shr:2 row_mask:0xf bank_mask:0xf
	v_mov_b32_dpp v184, v34 row_shr:1 row_mask:0xf bank_mask:0xf
	v_mov_b32_dpp v182, v98 row_shr:2 row_mask:0xf bank_mask:0xf
	v_mov_b32_dpp v180, v98 row_shr:1 row_mask:0xf bank_mask:0xf
	v_mov_b32_dpp v187, v35 row_shr:2 row_mask:0xf bank_mask:0xf
	v_mov_b32_dpp v185, v35 row_shr:1 row_mask:0xf bank_mask:0xf
	v_mov_b32_dpp v183, v99 row_shr:2 row_mask:0xf bank_mask:0xf
	v_mov_b32_dpp v181, v99 row_shr:1 row_mask:0xf bank_mask:0xf
	s_cmp_lg_u32 s42, 64
	s_cselect_b64 vcc, -1, s[40:41]
	s_and_saveexec_b64 s[0:1], vcc
	s_cbranch_execz .LBB0_627
	s_nop 0
	v_pk_fma_f32 v[194:195], v[146:147], v[194:195], v[158:159]
	v_pk_fma_f32 v[186:187], v[148:149], v[186:187], v[160:161]
	v_pk_fma_f32 v[192:193], v[150:151], v[192:193], v[194:195]
	v_pk_fma_f32 v[184:185], v[152:153], v[184:185], v[186:187]
	v_pk_fma_f32 v[192:193], v[32:33], v[154:155], v[192:193]
	v_pk_fma_f32 v[184:185], v[34:35], v[156:157], v[184:185]
	s_nop 0
	v_pk_fma_f32 v[190:191], v[130:131], v[190:191], v[142:143]
	v_pk_fma_f32 v[188:189], v[134:135], v[188:189], v[190:191]
	v_pk_mul_f32 v[210:211], v[192:193], v[192:193]
	v_pk_fma_f32 v[210:211], v[210:211], v[214:215], v[216:217]
	v_pk_mul_f32 v[210:211], v[210:211], v[192:193]
	v_exp_f32_e32 v210, v210
	v_exp_f32_e32 v211, v211
	s_nop 1
	v_pk_add_f32 v[210:211], v[210:211], v[218:219]
	v_rcp_f32_e32 v194, v210
	v_rcp_f32_e32 v195, v211
	s_nop 1
	v_pk_fma_f32 v[190:191], v[192:193], v[194:195], v[192:193] neg_lo:[1,0,0] neg_hi:[1,0,0]
	v_pk_fma_f32 v[188:189], v[96:97], v[138:139], v[188:189]
	v_pk_mul_f32 v[186:187], v[188:189], v[190:191]
	v_pk_fma_f32 v[182:183], v[132:133], v[182:183], v[144:145]
	s_nop 0
	v_pk_fma_f32 v[180:181], v[136:137], v[180:181], v[182:183]
	v_pk_mul_f32 v[210:211], v[184:185], v[184:185]
	v_pk_fma_f32 v[210:211], v[210:211], v[214:215], v[216:217]
	v_pk_mul_f32 v[210:211], v[210:211], v[184:185]
	v_exp_f32_e32 v210, v210
	v_exp_f32_e32 v211, v211
	s_nop 1
	v_pk_add_f32 v[210:211], v[210:211], v[218:219]
	v_rcp_f32_e32 v188, v210
	v_rcp_f32_e32 v189, v211
	s_nop 1
	v_pk_fma_f32 v[182:183], v[184:185], v[188:189], v[184:185] neg_lo:[1,0,0] neg_hi:[1,0,0]
	v_pk_fma_f32 v[180:181], v[98:99], v[140:141], v[180:181]
	s_nop 0
	v_pk_mul_f32 v[180:181], v[180:181], v[182:183]
	v_cvt_pk_bf16_f32 v182, v186, v187
	v_cvt_pk_bf16_f32 v183, v180, v181
	v_mad_i64_i32 v[180:181], s[6:7], v206, s5, v[178:179]
	global_store_dwordx2 v[180:181], v[182:183], off offset:8
.LBB0_627:
	s_or_b64 exec, exec, s[0:1]
	v_mov_b32_dpp v194, v24 row_shr:2 row_mask:0xf bank_mask:0xf bound_ctrl:1
	v_mov_b32_dpp v192, v24 row_shr:1 row_mask:0xf bank_mask:0xf bound_ctrl:1
	v_mov_b32_dpp v190, v88 row_shr:2 row_mask:0xf bank_mask:0xf bound_ctrl:1
	v_mov_b32_dpp v188, v88 row_shr:1 row_mask:0xf bank_mask:0xf bound_ctrl:1
	v_mov_b32_dpp v195, v25 row_shr:2 row_mask:0xf bank_mask:0xf bound_ctrl:1
	v_mov_b32_dpp v193, v25 row_shr:1 row_mask:0xf bank_mask:0xf bound_ctrl:1
	v_mov_b32_dpp v191, v89 row_shr:2 row_mask:0xf bank_mask:0xf bound_ctrl:1
	v_mov_b32_dpp v189, v89 row_shr:1 row_mask:0xf bank_mask:0xf bound_ctrl:1
	v_mov_b32_dpp v186, v26 row_shr:2 row_mask:0xf bank_mask:0xf bound_ctrl:1
	v_mov_b32_dpp v184, v26 row_shr:1 row_mask:0xf bank_mask:0xf bound_ctrl:1
	v_mov_b32_dpp v182, v90 row_shr:2 row_mask:0xf bank_mask:0xf bound_ctrl:1
	v_mov_b32_dpp v180, v90 row_shr:1 row_mask:0xf bank_mask:0xf bound_ctrl:1
	v_mov_b32_dpp v187, v27 row_shr:2 row_mask:0xf bank_mask:0xf bound_ctrl:1
	v_mov_b32_dpp v185, v27 row_shr:1 row_mask:0xf bank_mask:0xf bound_ctrl:1
	v_mov_b32_dpp v183, v91 row_shr:2 row_mask:0xf bank_mask:0xf bound_ctrl:1
	v_mov_b32_dpp v181, v91 row_shr:1 row_mask:0xf bank_mask:0xf bound_ctrl:1
	s_and_saveexec_b64 s[0:1], s[40:41]
	s_cbranch_execz .LBB0_629
	s_nop 0
	v_pk_fma_f32 v[194:195], v[146:147], v[194:195], v[158:159]
	v_pk_fma_f32 v[186:187], v[148:149], v[186:187], v[160:161]
	v_pk_fma_f32 v[192:193], v[150:151], v[192:193], v[194:195]
	v_pk_fma_f32 v[184:185], v[152:153], v[184:185], v[186:187]
	v_pk_fma_f32 v[192:193], v[24:25], v[154:155], v[192:193]
	v_pk_fma_f32 v[184:185], v[26:27], v[156:157], v[184:185]
	s_nop 0
	v_pk_fma_f32 v[190:191], v[130:131], v[190:191], v[142:143]
	v_pk_fma_f32 v[188:189], v[134:135], v[188:189], v[190:191]
	v_pk_mul_f32 v[210:211], v[192:193], v[192:193]
	v_pk_fma_f32 v[210:211], v[210:211], v[214:215], v[216:217]
	v_pk_mul_f32 v[210:211], v[210:211], v[192:193]
	v_exp_f32_e32 v210, v210
	v_exp_f32_e32 v211, v211
	s_nop 1
	v_pk_add_f32 v[210:211], v[210:211], v[218:219]
	v_rcp_f32_e32 v194, v210
	v_rcp_f32_e32 v195, v211
	s_nop 1
	v_pk_fma_f32 v[190:191], v[192:193], v[194:195], v[192:193] neg_lo:[1,0,0] neg_hi:[1,0,0]
	v_pk_fma_f32 v[188:189], v[88:89], v[138:139], v[188:189]
	v_pk_mul_f32 v[186:187], v[188:189], v[190:191]
	v_pk_fma_f32 v[182:183], v[132:133], v[182:183], v[144:145]
	s_nop 0
	v_pk_fma_f32 v[180:181], v[136:137], v[180:181], v[182:183]
	v_pk_mul_f32 v[210:211], v[184:185], v[184:185]
	v_pk_fma_f32 v[210:211], v[210:211], v[214:215], v[216:217]
	v_pk_mul_f32 v[210:211], v[210:211], v[184:185]
	v_exp_f32_e32 v210, v210
	v_exp_f32_e32 v211, v211
	s_nop 1
	v_pk_add_f32 v[210:211], v[210:211], v[218:219]
	v_rcp_f32_e32 v188, v210
	v_rcp_f32_e32 v189, v211
	s_nop 1
	v_pk_fma_f32 v[182:183], v[184:185], v[188:189], v[184:185] neg_lo:[1,0,0] neg_hi:[1,0,0]
	v_pk_fma_f32 v[180:181], v[90:91], v[140:141], v[180:181]
	s_nop 0
	v_pk_mul_f32 v[180:181], v[180:181], v[182:183]
	v_cvt_pk_bf16_f32 v182, v186, v187
	v_cvt_pk_bf16_f32 v183, v180, v181
	v_mad_i64_i32 v[180:181], s[6:7], v173, s5, v[178:179]
	global_store_dwordx2 v[180:181], v[182:183], off offset:8
.LBB0_629:
	s_or_b64 exec, exec, s[0:1]
	s_cmp_lg_u32 s42, 64
	s_cselect_b64 exec, -1, 0
	s_nop 1
	v_mov_b32_dpp v194, v24 row_ror:2 row_mask:0xf bank_mask:0x1
	v_mov_b32_dpp v192, v24 row_ror:1 row_mask:0xf bank_mask:0x1
	v_mov_b32_dpp v190, v88 row_ror:2 row_mask:0xf bank_mask:0x1
	v_mov_b32_dpp v188, v88 row_ror:1 row_mask:0xf bank_mask:0x1
	v_mov_b32_dpp v195, v25 row_ror:2 row_mask:0xf bank_mask:0x1
	v_mov_b32_dpp v193, v25 row_ror:1 row_mask:0xf bank_mask:0x1
	v_mov_b32_dpp v191, v89 row_ror:2 row_mask:0xf bank_mask:0x1
	v_mov_b32_dpp v189, v89 row_ror:1 row_mask:0xf bank_mask:0x1
	v_mov_b32_dpp v186, v26 row_ror:2 row_mask:0xf bank_mask:0x1
	v_mov_b32_dpp v184, v26 row_ror:1 row_mask:0xf bank_mask:0x1
	v_mov_b32_dpp v182, v90 row_ror:2 row_mask:0xf bank_mask:0x1
	v_mov_b32_dpp v180, v90 row_ror:1 row_mask:0xf bank_mask:0x1
	v_mov_b32_dpp v187, v27 row_ror:2 row_mask:0xf bank_mask:0x1
	v_mov_b32_dpp v185, v27 row_ror:1 row_mask:0xf bank_mask:0x1
	v_mov_b32_dpp v183, v91 row_ror:2 row_mask:0xf bank_mask:0x1
	v_mov_b32_dpp v181, v91 row_ror:1 row_mask:0xf bank_mask:0x1
	s_mov_b64 exec, -1
	s_nop 1
	v_mov_b32_dpp v194, v16 row_shr:2 row_mask:0xf bank_mask:0xf
	v_mov_b32_dpp v192, v16 row_shr:1 row_mask:0xf bank_mask:0xf
	v_mov_b32_dpp v190, v80 row_shr:2 row_mask:0xf bank_mask:0xf
	v_mov_b32_dpp v188, v80 row_shr:1 row_mask:0xf bank_mask:0xf
	v_mov_b32_dpp v195, v17 row_shr:2 row_mask:0xf bank_mask:0xf
	v_mov_b32_dpp v193, v17 row_shr:1 row_mask:0xf bank_mask:0xf
	v_mov_b32_dpp v191, v81 row_shr:2 row_mask:0xf bank_mask:0xf
	v_mov_b32_dpp v189, v81 row_shr:1 row_mask:0xf bank_mask:0xf
	v_mov_b32_dpp v186, v18 row_shr:2 row_mask:0xf bank_mask:0xf
	v_mov_b32_dpp v184, v18 row_shr:1 row_mask:0xf bank_mask:0xf
	v_mov_b32_dpp v182, v82 row_shr:2 row_mask:0xf bank_mask:0xf
	v_mov_b32_dpp v180, v82 row_shr:1 row_mask:0xf bank_mask:0xf
	v_mov_b32_dpp v187, v19 row_shr:2 row_mask:0xf bank_mask:0xf
	v_mov_b32_dpp v185, v19 row_shr:1 row_mask:0xf bank_mask:0xf
	v_mov_b32_dpp v183, v83 row_shr:2 row_mask:0xf bank_mask:0xf
	v_mov_b32_dpp v181, v83 row_shr:1 row_mask:0xf bank_mask:0xf
	s_cmp_lg_u32 s42, 64
	s_cselect_b64 vcc, -1, s[40:41]
	s_and_saveexec_b64 s[0:1], vcc
	s_cbranch_execz .LBB0_631
	s_nop 0
	v_pk_fma_f32 v[194:195], v[146:147], v[194:195], v[158:159]
	v_pk_fma_f32 v[186:187], v[148:149], v[186:187], v[160:161]
	v_pk_fma_f32 v[192:193], v[150:151], v[192:193], v[194:195]
	v_pk_fma_f32 v[184:185], v[152:153], v[184:185], v[186:187]
	v_pk_fma_f32 v[192:193], v[16:17], v[154:155], v[192:193]
	v_pk_fma_f32 v[184:185], v[18:19], v[156:157], v[184:185]
	s_nop 0
	v_pk_fma_f32 v[190:191], v[130:131], v[190:191], v[142:143]
	v_pk_fma_f32 v[188:189], v[134:135], v[188:189], v[190:191]
	v_pk_mul_f32 v[210:211], v[192:193], v[192:193]
	v_pk_fma_f32 v[210:211], v[210:211], v[214:215], v[216:217]
	v_pk_mul_f32 v[210:211], v[210:211], v[192:193]
	v_exp_f32_e32 v210, v210
	v_exp_f32_e32 v211, v211
	s_nop 1
	v_pk_add_f32 v[210:211], v[210:211], v[218:219]
	v_rcp_f32_e32 v194, v210
	v_rcp_f32_e32 v195, v211
	s_nop 1
	v_pk_fma_f32 v[190:191], v[192:193], v[194:195], v[192:193] neg_lo:[1,0,0] neg_hi:[1,0,0]
	v_pk_fma_f32 v[188:189], v[80:81], v[138:139], v[188:189]
	v_pk_mul_f32 v[186:187], v[188:189], v[190:191]
	v_pk_fma_f32 v[182:183], v[132:133], v[182:183], v[144:145]
	s_nop 0
	v_pk_fma_f32 v[180:181], v[136:137], v[180:181], v[182:183]
	v_pk_mul_f32 v[210:211], v[184:185], v[184:185]
	v_pk_fma_f32 v[210:211], v[210:211], v[214:215], v[216:217]
	v_pk_mul_f32 v[210:211], v[210:211], v[184:185]
	v_exp_f32_e32 v210, v210
	v_exp_f32_e32 v211, v211
	s_nop 1
	v_pk_add_f32 v[210:211], v[210:211], v[218:219]
	v_rcp_f32_e32 v188, v210
	v_rcp_f32_e32 v189, v211
	s_nop 1
	v_pk_fma_f32 v[182:183], v[184:185], v[188:189], v[184:185] neg_lo:[1,0,0] neg_hi:[1,0,0]
	v_pk_fma_f32 v[180:181], v[82:83], v[140:141], v[180:181]
	s_nop 0
	v_pk_mul_f32 v[180:181], v[180:181], v[182:183]
	v_cvt_pk_bf16_f32 v182, v186, v187
	v_cvt_pk_bf16_f32 v183, v180, v181
	v_mad_i64_i32 v[180:181], s[6:7], v207, s5, v[178:179]
	global_store_dwordx2 v[180:181], v[182:183], off offset:8
.LBB0_631:
	s_or_b64 exec, exec, s[0:1]
	s_cmp_lg_u32 s42, 64
	s_cselect_b64 exec, -1, 0
	s_nop 1
	v_mov_b32_dpp v194, v16 row_ror:2 row_mask:0xf bank_mask:0x1
	v_mov_b32_dpp v192, v16 row_ror:1 row_mask:0xf bank_mask:0x1
	v_mov_b32_dpp v190, v80 row_ror:2 row_mask:0xf bank_mask:0x1
	v_mov_b32_dpp v188, v80 row_ror:1 row_mask:0xf bank_mask:0x1
	v_mov_b32_dpp v195, v17 row_ror:2 row_mask:0xf bank_mask:0x1
	v_mov_b32_dpp v193, v17 row_ror:1 row_mask:0xf bank_mask:0x1
	v_mov_b32_dpp v191, v81 row_ror:2 row_mask:0xf bank_mask:0x1
	v_mov_b32_dpp v189, v81 row_ror:1 row_mask:0xf bank_mask:0x1
	v_mov_b32_dpp v186, v18 row_ror:2 row_mask:0xf bank_mask:0x1
	v_mov_b32_dpp v184, v18 row_ror:1 row_mask:0xf bank_mask:0x1
	v_mov_b32_dpp v182, v82 row_ror:2 row_mask:0xf bank_mask:0x1
	v_mov_b32_dpp v180, v82 row_ror:1 row_mask:0xf bank_mask:0x1
	v_mov_b32_dpp v187, v19 row_ror:2 row_mask:0xf bank_mask:0x1
	v_mov_b32_dpp v185, v19 row_ror:1 row_mask:0xf bank_mask:0x1
	v_mov_b32_dpp v183, v83 row_ror:2 row_mask:0xf bank_mask:0x1
	v_mov_b32_dpp v181, v83 row_ror:1 row_mask:0xf bank_mask:0x1
	s_mov_b64 exec, -1
	s_nop 1
	v_mov_b32_dpp v194, v8 row_shr:2 row_mask:0xf bank_mask:0xf
	v_mov_b32_dpp v192, v8 row_shr:1 row_mask:0xf bank_mask:0xf
	v_mov_b32_dpp v190, v72 row_shr:2 row_mask:0xf bank_mask:0xf
	v_mov_b32_dpp v188, v72 row_shr:1 row_mask:0xf bank_mask:0xf
	v_mov_b32_dpp v195, v9 row_shr:2 row_mask:0xf bank_mask:0xf
	v_mov_b32_dpp v193, v9 row_shr:1 row_mask:0xf bank_mask:0xf
	v_mov_b32_dpp v191, v73 row_shr:2 row_mask:0xf bank_mask:0xf
	v_mov_b32_dpp v189, v73 row_shr:1 row_mask:0xf bank_mask:0xf
	v_mov_b32_dpp v186, v10 row_shr:2 row_mask:0xf bank_mask:0xf
	v_mov_b32_dpp v184, v10 row_shr:1 row_mask:0xf bank_mask:0xf
	v_mov_b32_dpp v182, v74 row_shr:2 row_mask:0xf bank_mask:0xf
	v_mov_b32_dpp v180, v74 row_shr:1 row_mask:0xf bank_mask:0xf
	v_mov_b32_dpp v187, v11 row_shr:2 row_mask:0xf bank_mask:0xf
	v_mov_b32_dpp v185, v11 row_shr:1 row_mask:0xf bank_mask:0xf
	v_mov_b32_dpp v183, v75 row_shr:2 row_mask:0xf bank_mask:0xf
	v_mov_b32_dpp v181, v75 row_shr:1 row_mask:0xf bank_mask:0xf
	s_cmp_lg_u32 s42, 64
	s_cselect_b64 vcc, -1, s[40:41]
	s_and_saveexec_b64 s[0:1], vcc
	s_cbranch_execz .LBB0_633
	s_nop 0
	v_pk_fma_f32 v[194:195], v[146:147], v[194:195], v[158:159]
	v_pk_fma_f32 v[186:187], v[148:149], v[186:187], v[160:161]
	v_pk_fma_f32 v[192:193], v[150:151], v[192:193], v[194:195]
	v_pk_fma_f32 v[184:185], v[152:153], v[184:185], v[186:187]
	v_pk_fma_f32 v[192:193], v[8:9], v[154:155], v[192:193]
	v_pk_fma_f32 v[184:185], v[10:11], v[156:157], v[184:185]
	s_nop 0
	v_pk_fma_f32 v[190:191], v[130:131], v[190:191], v[142:143]
	v_pk_fma_f32 v[188:189], v[134:135], v[188:189], v[190:191]
	v_pk_mul_f32 v[210:211], v[192:193], v[192:193]
	v_pk_fma_f32 v[210:211], v[210:211], v[214:215], v[216:217]
	v_pk_mul_f32 v[210:211], v[210:211], v[192:193]
	v_exp_f32_e32 v210, v210
	v_exp_f32_e32 v211, v211
	s_nop 1
	v_pk_add_f32 v[210:211], v[210:211], v[218:219]
	v_rcp_f32_e32 v194, v210
	v_rcp_f32_e32 v195, v211
	s_nop 1
	v_pk_fma_f32 v[190:191], v[192:193], v[194:195], v[192:193] neg_lo:[1,0,0] neg_hi:[1,0,0]
	v_pk_fma_f32 v[188:189], v[72:73], v[138:139], v[188:189]
	v_pk_mul_f32 v[186:187], v[188:189], v[190:191]
	v_pk_fma_f32 v[182:183], v[132:133], v[182:183], v[144:145]
	s_nop 0
	v_pk_fma_f32 v[180:181], v[136:137], v[180:181], v[182:183]
	v_pk_mul_f32 v[210:211], v[184:185], v[184:185]
	v_pk_fma_f32 v[210:211], v[210:211], v[214:215], v[216:217]
	v_pk_mul_f32 v[210:211], v[210:211], v[184:185]
	v_exp_f32_e32 v210, v210
	v_exp_f32_e32 v211, v211
	s_nop 1
	v_pk_add_f32 v[210:211], v[210:211], v[218:219]
	v_rcp_f32_e32 v188, v210
	v_rcp_f32_e32 v189, v211
	s_nop 1
	v_pk_fma_f32 v[182:183], v[184:185], v[188:189], v[184:185] neg_lo:[1,0,0] neg_hi:[1,0,0]
	v_pk_fma_f32 v[180:181], v[74:75], v[140:141], v[180:181]
	s_nop 0
	v_pk_mul_f32 v[180:181], v[180:181], v[182:183]
	v_cvt_pk_bf16_f32 v182, v186, v187
	v_cvt_pk_bf16_f32 v183, v180, v181
	v_mad_i64_i32 v[180:181], s[6:7], v208, s5, v[178:179]
	global_store_dwordx2 v[180:181], v[182:183], off offset:8
.LBB0_633:
	s_or_b64 exec, exec, s[0:1]
	s_cmp_lg_u32 s42, 64
	s_cselect_b64 exec, -1, 0
	s_nop 1
	v_mov_b32_dpp v194, v8 row_ror:2 row_mask:0xf bank_mask:0x1
	v_mov_b32_dpp v192, v8 row_ror:1 row_mask:0xf bank_mask:0x1
	v_mov_b32_dpp v190, v72 row_ror:2 row_mask:0xf bank_mask:0x1
	v_mov_b32_dpp v188, v72 row_ror:1 row_mask:0xf bank_mask:0x1
	v_mov_b32_dpp v195, v9 row_ror:2 row_mask:0xf bank_mask:0x1
	v_mov_b32_dpp v193, v9 row_ror:1 row_mask:0xf bank_mask:0x1
	v_mov_b32_dpp v191, v73 row_ror:2 row_mask:0xf bank_mask:0x1
	v_mov_b32_dpp v189, v73 row_ror:1 row_mask:0xf bank_mask:0x1
	v_mov_b32_dpp v186, v10 row_ror:2 row_mask:0xf bank_mask:0x1
	v_mov_b32_dpp v184, v10 row_ror:1 row_mask:0xf bank_mask:0x1
	v_mov_b32_dpp v182, v74 row_ror:2 row_mask:0xf bank_mask:0x1
	v_mov_b32_dpp v180, v74 row_ror:1 row_mask:0xf bank_mask:0x1
	v_mov_b32_dpp v187, v11 row_ror:2 row_mask:0xf bank_mask:0x1
	v_mov_b32_dpp v185, v11 row_ror:1 row_mask:0xf bank_mask:0x1
	v_mov_b32_dpp v183, v75 row_ror:2 row_mask:0xf bank_mask:0x1
	v_mov_b32_dpp v181, v75 row_ror:1 row_mask:0xf bank_mask:0x1
	s_mov_b64 exec, -1
	s_nop 1
	v_mov_b32_dpp v194, v0 row_shr:2 row_mask:0xf bank_mask:0xf
	v_mov_b32_dpp v192, v0 row_shr:1 row_mask:0xf bank_mask:0xf
	v_mov_b32_dpp v190, v60 row_shr:2 row_mask:0xf bank_mask:0xf
	v_mov_b32_dpp v188, v60 row_shr:1 row_mask:0xf bank_mask:0xf
	v_mov_b32_dpp v195, v1 row_shr:2 row_mask:0xf bank_mask:0xf
	v_mov_b32_dpp v193, v1 row_shr:1 row_mask:0xf bank_mask:0xf
	v_mov_b32_dpp v191, v61 row_shr:2 row_mask:0xf bank_mask:0xf
	v_mov_b32_dpp v189, v61 row_shr:1 row_mask:0xf bank_mask:0xf
	v_mov_b32_dpp v186, v2 row_shr:2 row_mask:0xf bank_mask:0xf
	v_mov_b32_dpp v184, v2 row_shr:1 row_mask:0xf bank_mask:0xf
	v_mov_b32_dpp v182, v62 row_shr:2 row_mask:0xf bank_mask:0xf
	v_mov_b32_dpp v180, v62 row_shr:1 row_mask:0xf bank_mask:0xf
	v_mov_b32_dpp v187, v3 row_shr:2 row_mask:0xf bank_mask:0xf
	v_mov_b32_dpp v185, v3 row_shr:1 row_mask:0xf bank_mask:0xf
	v_mov_b32_dpp v183, v63 row_shr:2 row_mask:0xf bank_mask:0xf
	v_mov_b32_dpp v181, v63 row_shr:1 row_mask:0xf bank_mask:0xf
	s_cmp_lg_u32 s42, 64
	s_cselect_b64 vcc, -1, s[40:41]
	s_and_saveexec_b64 s[0:1], vcc
	s_cbranch_execz .LBB0_635
	s_nop 0
	v_pk_fma_f32 v[146:147], v[146:147], v[194:195], v[158:159]
	s_nop 0
	v_pk_fma_f32 v[130:131], v[130:131], v[190:191], v[142:143]
	v_pk_fma_f32 v[146:147], v[150:151], v[192:193], v[146:147]
	v_pk_fma_f32 v[130:131], v[134:135], v[188:189], v[130:131]
	v_pk_fma_f32 v[146:147], v[0:1], v[154:155], v[146:147]
	v_pk_fma_f32 v[130:131], v[60:61], v[138:139], v[130:131]
	v_pk_fma_f32 v[138:139], v[148:149], v[186:187], v[160:161]
	v_pk_fma_f32 v[132:133], v[132:133], v[182:183], v[144:145]
	v_pk_fma_f32 v[138:139], v[152:153], v[184:185], v[138:139]
	v_pk_fma_f32 v[138:139], v[2:3], v[156:157], v[138:139]
	v_pk_mul_f32 v[210:211], v[146:147], v[146:147]
	v_pk_fma_f32 v[210:211], v[210:211], v[214:215], v[216:217]
	v_pk_mul_f32 v[210:211], v[210:211], v[146:147]
	v_exp_f32_e32 v210, v210
	v_exp_f32_e32 v211, v211
	s_nop 1
	v_pk_add_f32 v[210:211], v[210:211], v[218:219]
	v_rcp_f32_e32 v150, v210
	v_rcp_f32_e32 v151, v211
	s_nop 1
	v_pk_fma_f32 v[134:135], v[146:147], v[150:151], v[146:147] neg_lo:[1,0,0] neg_hi:[1,0,0]
	v_pk_fma_f32 v[132:133], v[136:137], v[180:181], v[132:133]
	v_pk_mul_f32 v[130:131], v[130:131], v[134:135]
	v_pk_fma_f32 v[132:133], v[62:63], v[140:141], v[132:133]
	v_cvt_pk_bf16_f32 v130, v130, v131
	v_pk_mul_f32 v[210:211], v[138:139], v[138:139]
	v_pk_fma_f32 v[210:211], v[210:211], v[214:215], v[216:217]
	v_pk_mul_f32 v[210:211], v[210:211], v[138:139]
	v_exp_f32_e32 v210, v210
	v_exp_f32_e32 v211, v211
	s_nop 1
	v_pk_add_f32 v[210:211], v[210:211], v[218:219]
	v_rcp_f32_e32 v134, v210
	v_rcp_f32_e32 v135, v211
	s_nop 1
	v_pk_fma_f32 v[134:135], v[138:139], v[134:135], v[138:139] neg_lo:[1,0,0] neg_hi:[1,0,0]
	s_nop 0
	v_pk_mul_f32 v[132:133], v[132:133], v[134:135]
	s_nop 0
	v_cvt_pk_bf16_f32 v131, v132, v133
	v_mad_i64_i32 v[132:133], s[6:7], v209, s5, v[178:179]
	global_store_dwordx2 v[132:133], v[130:131], off offset:8
